# scan consumer chunk loop: every 8-byte instruction padded to 8-byte alignment (74 s_nop 0), deferred group-3 transposes
# speedup vs baseline: 1.0159x; 1.0039x over previous
.Lscan_cons_chunk:
	s_nop 0
	v_cndmask_b32_e64 v2, v4, v5, s[42:43]
	v_add_lshl_u32 v2, v2, s80, 10
	v_mov_b32_e32 v3, v180
	s_nop 0
	s_add_i32 s28, s28, 0x10000
	v_lshl_add_u64 v[2:3], v[0:1], 0, v[2:3]
	v_add_u32_e32 v5, 64, v5
	v_subrev_u32_e32 v4, 64, v4
	s_waitcnt lgkmcnt(3)
	s_nop 0
	v_fma_mix_f32 v12, v6, v20, v180 op_sel_hi:[0,1,0]
	v_fma_mix_f32 v12, v7, v20, v12 op_sel:[0,1,0] op_sel_hi:[0,1,0]
	v_fma_mix_f32 v12, v8, v21, v12 op_sel_hi:[0,1,0]
	v_fma_mix_f32 v12, v9, v21, v12 op_sel:[0,1,0] op_sel_hi:[0,1,0]
	s_nop 1
	s_nop 0
	v_add_f32_dpp v12, v12, v12 row_ror:1 row_mask:0xf bank_mask:0xf bound_ctrl:1
	s_nop 1
	s_nop 0
	v_add_f32_dpp v12, v12, v12 row_ror:2 row_mask:0xf bank_mask:0xf bound_ctrl:1
	v_pk_fma_f32 v[48:49], v[28:29], v[66:67], v[6:7] op_sel_hi:[1,0,1]
	v_pk_fma_f32 v[50:51], v[30:31], v[66:67], v[8:9] op_sel_hi:[1,0,1]
	v_add_f32_dpp v12, v12, v12 row_ror:4 row_mask:0xf bank_mask:0xf bound_ctrl:1
	v_add_f32_dpp v130, v130, v130 row_ror:8 row_mask:0xf bank_mask:0xc
	v_add_f32_dpp v130, v122, v122 row_ror:8 row_mask:0xf bank_mask:0x3
	v_add_f32_dpp v131, v131, v131 row_ror:8 row_mask:0xf bank_mask:0xc
	v_add_f32_dpp v12, v12, v12 row_ror:8 row_mask:0xf bank_mask:0xf bound_ctrl:1
	v_pk_fma_f32 v[6:7], v[24:25], v[12:13], v[48:49] op_sel_hi:[1,0,1] neg_lo:[1,0,0] neg_hi:[1,0,0]
	v_pk_fma_f32 v[8:9], v[26:27], v[12:13], v[50:51] op_sel_hi:[1,0,1] neg_lo:[1,0,0] neg_hi:[1,0,0]
	ds_read_b128 v[88:91], v10 offset:2304
	ds_read_b128 v[96:99], v10 offset:2816
	ds_read_b128 v[92:95], v10 offset:2560
	s_waitcnt lgkmcnt(3)
	s_nop 0
	v_fma_mix_f32 v12, v6, v36, v180 op_sel_hi:[0,1,0]
	v_fma_mix_f32 v12, v7, v36, v12 op_sel:[0,1,0] op_sel_hi:[0,1,0]
	v_fma_mix_f32 v12, v8, v37, v12 op_sel_hi:[0,1,0]
	v_fma_mix_f32 v12, v9, v37, v12 op_sel:[0,1,0] op_sel_hi:[0,1,0]
	v_fma_mix_f32 v52, v6, v22, v180 op_sel_hi:[0,1,0]
	v_fma_mix_f32 v52, v7, v22, v52 op_sel:[0,1,0] op_sel_hi:[0,1,0]
	v_add_f32_dpp v12, v12, v12 row_ror:1 row_mask:0xf bank_mask:0xf bound_ctrl:1
	v_fma_mix_f32 v52, v8, v23, v52 op_sel_hi:[0,1,0]
	v_fma_mix_f32 v52, v9, v23, v52 op_sel:[0,1,0] op_sel_hi:[0,1,0]
	v_add_f32_dpp v12, v12, v12 row_ror:2 row_mask:0xf bank_mask:0xf bound_ctrl:1
	v_pk_fma_f32 v[48:49], v[44:45], v[66:67], v[6:7] op_sel:[0,1,0]
	v_pk_fma_f32 v[50:51], v[46:47], v[66:67], v[8:9] op_sel:[0,1,0]
	v_add_f32_dpp v12, v12, v12 row_ror:4 row_mask:0xf bank_mask:0xf bound_ctrl:1
	v_add_f32_dpp v131, v123, v123 row_ror:8 row_mask:0xf bank_mask:0x3
	v_add_f32_dpp v132, v132, v132 row_ror:8 row_mask:0xf bank_mask:0xc
	v_add_f32_dpp v132, v124, v124 row_ror:8 row_mask:0xf bank_mask:0x3
	v_add_f32_dpp v12, v12, v12 row_ror:8 row_mask:0xf bank_mask:0xf bound_ctrl:1
	v_pk_fma_f32 v[6:7], v[40:41], v[12:13], v[48:49] op_sel_hi:[1,0,1] neg_lo:[1,0,0] neg_hi:[1,0,0]
	v_pk_fma_f32 v[8:9], v[42:43], v[12:13], v[50:51] op_sel_hi:[1,0,1] neg_lo:[1,0,0] neg_hi:[1,0,0]
	ds_read_b128 v[110:113], v10 offset:3328
	ds_read_b128 v[106:109], v10 offset:3072
	ds_read_b128 v[118:121], v10 offset:3840
	ds_read_b128 v[114:117], v10 offset:3584
	ds_read_b128 v[70:73], v11 offset:256
	s_waitcnt lgkmcnt(5)
	s_nop 0
	v_fma_mix_f32 v12, v6, v88, v180 op_sel_hi:[0,1,0]
	v_fma_mix_f32 v12, v7, v88, v12 op_sel:[0,1,0] op_sel_hi:[0,1,0]
	v_fma_mix_f32 v12, v8, v89, v12 op_sel_hi:[0,1,0]
	v_fma_mix_f32 v12, v9, v89, v12 op_sel:[0,1,0] op_sel_hi:[0,1,0]
	v_fma_mix_f32 v53, v6, v38, v180 op_sel_hi:[0,1,0]
	v_fma_mix_f32 v53, v7, v38, v53 op_sel:[0,1,0] op_sel_hi:[0,1,0]
	v_add_f32_dpp v12, v12, v12 row_ror:1 row_mask:0xf bank_mask:0xf bound_ctrl:1
	v_fma_mix_f32 v53, v8, v39, v53 op_sel_hi:[0,1,0]
	v_fma_mix_f32 v53, v9, v39, v53 op_sel:[0,1,0] op_sel_hi:[0,1,0]
	v_add_f32_dpp v12, v12, v12 row_ror:2 row_mask:0xf bank_mask:0xf bound_ctrl:1
	v_pk_fma_f32 v[48:49], v[96:97], v[68:69], v[6:7] op_sel_hi:[1,0,1]
	v_pk_fma_f32 v[50:51], v[98:99], v[68:69], v[8:9] op_sel_hi:[1,0,1]
	v_add_f32_dpp v12, v12, v12 row_ror:4 row_mask:0xf bank_mask:0xf bound_ctrl:1
	v_add_f32_dpp v133, v133, v133 row_ror:8 row_mask:0xf bank_mask:0xc
	v_add_f32_dpp v133, v125, v125 row_ror:8 row_mask:0xf bank_mask:0x3
	v_add_f32_dpp v134, v134, v134 row_ror:8 row_mask:0xf bank_mask:0xc
	v_add_f32_dpp v12, v12, v12 row_ror:8 row_mask:0xf bank_mask:0xf bound_ctrl:1
	v_pk_fma_f32 v[6:7], v[92:93], v[12:13], v[48:49] op_sel_hi:[1,0,1] neg_lo:[1,0,0] neg_hi:[1,0,0]
	v_pk_fma_f32 v[8:9], v[94:95], v[12:13], v[50:51] op_sel_hi:[1,0,1] neg_lo:[1,0,0] neg_hi:[1,0,0]
	ds_read_b128 v[20:23], v10 offset:4352
	ds_read_b128 v[28:31], v10 offset:4864
	ds_read_b128 v[24:27], v10 offset:4608
	s_waitcnt lgkmcnt(4)
	s_nop 0
	v_fma_mix_f32 v12, v6, v110, v180 op_sel_hi:[0,1,0]
	v_fma_mix_f32 v12, v7, v110, v12 op_sel:[0,1,0] op_sel_hi:[0,1,0]
	v_fma_mix_f32 v12, v8, v111, v12 op_sel_hi:[0,1,0]
	v_fma_mix_f32 v12, v9, v111, v12 op_sel:[0,1,0] op_sel_hi:[0,1,0]
	v_fma_mix_f32 v54, v6, v90, v180 op_sel_hi:[0,1,0]
	v_fma_mix_f32 v54, v7, v90, v54 op_sel:[0,1,0] op_sel_hi:[0,1,0]
	v_add_f32_dpp v12, v12, v12 row_ror:1 row_mask:0xf bank_mask:0xf bound_ctrl:1
	v_fma_mix_f32 v54, v8, v91, v54 op_sel_hi:[0,1,0]
	v_fma_mix_f32 v54, v9, v91, v54 op_sel:[0,1,0] op_sel_hi:[0,1,0]
	v_add_f32_dpp v12, v12, v12 row_ror:2 row_mask:0xf bank_mask:0xf bound_ctrl:1
	v_pk_fma_f32 v[48:49], v[118:119], v[68:69], v[6:7] op_sel:[0,1,0]
	v_pk_fma_f32 v[50:51], v[120:121], v[68:69], v[8:9] op_sel:[0,1,0]
	v_add_f32_dpp v12, v12, v12 row_ror:4 row_mask:0xf bank_mask:0xf bound_ctrl:1
	v_add_f32_dpp v134, v126, v126 row_ror:8 row_mask:0xf bank_mask:0x3
	v_add_f32_dpp v135, v135, v135 row_ror:8 row_mask:0xf bank_mask:0xc
	v_add_f32_dpp v135, v127, v127 row_ror:8 row_mask:0xf bank_mask:0x3
	v_add_f32_dpp v12, v12, v12 row_ror:8 row_mask:0xf bank_mask:0xf bound_ctrl:1
	v_pk_fma_f32 v[6:7], v[114:115], v[12:13], v[48:49] op_sel_hi:[1,0,1] neg_lo:[1,0,0] neg_hi:[1,0,0]
	v_pk_fma_f32 v[8:9], v[116:117], v[12:13], v[50:51] op_sel_hi:[1,0,1] neg_lo:[1,0,0] neg_hi:[1,0,0]
	v_pk_mul_f32 v[6:7], v[6:7], v[106:107]
	v_pk_mul_f32 v[8:9], v[8:9], v[108:109]
	ds_read_b128 v[36:39], v10 offset:5376
	ds_read_b128 v[44:47], v10 offset:5888
	ds_read_b128 v[40:43], v10 offset:5632
	s_waitcnt lgkmcnt(3)
	s_nop 0
	v_fma_mix_f32 v12, v6, v20, v180 op_sel_hi:[0,1,0]
	v_fma_mix_f32 v12, v7, v20, v12 op_sel:[0,1,0] op_sel_hi:[0,1,0]
	v_fma_mix_f32 v12, v8, v21, v12 op_sel_hi:[0,1,0]
	v_fma_mix_f32 v12, v9, v21, v12 op_sel:[0,1,0] op_sel_hi:[0,1,0]
	v_fma_mix_f32 v55, v6, v112, v180 op_sel_hi:[0,1,0]
	v_fma_mix_f32 v55, v7, v112, v55 op_sel:[0,1,0] op_sel_hi:[0,1,0]
	v_add_f32_dpp v12, v12, v12 row_ror:1 row_mask:0xf bank_mask:0xf bound_ctrl:1
	v_fma_mix_f32 v55, v8, v113, v55 op_sel_hi:[0,1,0]
	v_fma_mix_f32 v55, v9, v113, v55 op_sel:[0,1,0] op_sel_hi:[0,1,0]
	v_add_f32_dpp v12, v12, v12 row_ror:2 row_mask:0xf bank_mask:0xf bound_ctrl:1
	v_pk_fma_f32 v[48:49], v[28:29], v[70:71], v[6:7] op_sel_hi:[1,0,1]
	v_pk_fma_f32 v[50:51], v[30:31], v[70:71], v[8:9] op_sel_hi:[1,0,1]
	v_add_f32_dpp v12, v12, v12 row_ror:4 row_mask:0xf bank_mask:0xf bound_ctrl:1
	v_add_f32_dpp v136, v136, v136 row_ror:8 row_mask:0xf bank_mask:0xc
	v_add_f32_dpp v136, v128, v128 row_ror:8 row_mask:0xf bank_mask:0x3
	v_add_f32_dpp v12, v12, v12 row_ror:8 row_mask:0xf bank_mask:0xf bound_ctrl:1
	v_pk_fma_f32 v[6:7], v[24:25], v[12:13], v[48:49] op_sel_hi:[1,0,1] neg_lo:[1,0,0] neg_hi:[1,0,0]
	v_pk_fma_f32 v[8:9], v[26:27], v[12:13], v[50:51] op_sel_hi:[1,0,1] neg_lo:[1,0,0] neg_hi:[1,0,0]
	ds_read_b128 v[88:91], v10 offset:6400
	ds_read_b128 v[96:99], v10 offset:6912
	ds_read_b128 v[92:95], v10 offset:6656
	s_waitcnt lgkmcnt(3)
	s_nop 0
	v_fma_mix_f32 v12, v6, v36, v180 op_sel_hi:[0,1,0]
	v_fma_mix_f32 v12, v7, v36, v12 op_sel:[0,1,0] op_sel_hi:[0,1,0]
	v_fma_mix_f32 v12, v8, v37, v12 op_sel_hi:[0,1,0]
	v_fma_mix_f32 v12, v9, v37, v12 op_sel:[0,1,0] op_sel_hi:[0,1,0]
	v_fma_mix_f32 v56, v6, v22, v180 op_sel_hi:[0,1,0]
	v_fma_mix_f32 v56, v7, v22, v56 op_sel:[0,1,0] op_sel_hi:[0,1,0]
	v_add_f32_dpp v12, v12, v12 row_ror:1 row_mask:0xf bank_mask:0xf bound_ctrl:1
	v_fma_mix_f32 v56, v8, v23, v56 op_sel_hi:[0,1,0]
	v_fma_mix_f32 v56, v9, v23, v56 op_sel:[0,1,0] op_sel_hi:[0,1,0]
	v_add_f32_dpp v12, v12, v12 row_ror:2 row_mask:0xf bank_mask:0xf bound_ctrl:1
	v_pk_fma_f32 v[48:49], v[44:45], v[70:71], v[6:7] op_sel:[0,1,0]
	v_pk_fma_f32 v[50:51], v[46:47], v[70:71], v[8:9] op_sel:[0,1,0]
	v_add_f32_dpp v12, v12, v12 row_ror:4 row_mask:0xf bank_mask:0xf bound_ctrl:1
	v_add_f32_dpp v137, v137, v137 row_ror:8 row_mask:0xf bank_mask:0xc
	v_add_f32_dpp v137, v129, v129 row_ror:8 row_mask:0xf bank_mask:0x3
	v_add_f32_dpp v12, v12, v12 row_ror:8 row_mask:0xf bank_mask:0xf bound_ctrl:1
	v_pk_fma_f32 v[6:7], v[40:41], v[12:13], v[48:49] op_sel_hi:[1,0,1] neg_lo:[1,0,0] neg_hi:[1,0,0]
	v_pk_fma_f32 v[8:9], v[42:43], v[12:13], v[50:51] op_sel_hi:[1,0,1] neg_lo:[1,0,0] neg_hi:[1,0,0]
	ds_read_b128 v[110:113], v10 offset:7424
	ds_read_b128 v[106:109], v10 offset:7168
	ds_read_b128 v[118:121], v10 offset:7936
	ds_read_b128 v[114:117], v10 offset:7680
	ds_read_b128 v[66:69], v11 offset:512
	s_waitcnt lgkmcnt(5)
	s_nop 0
	v_fma_mix_f32 v12, v6, v88, v180 op_sel_hi:[0,1,0]
	v_fma_mix_f32 v12, v7, v88, v12 op_sel:[0,1,0] op_sel_hi:[0,1,0]
	v_fma_mix_f32 v12, v8, v89, v12 op_sel_hi:[0,1,0]
	v_fma_mix_f32 v12, v9, v89, v12 op_sel:[0,1,0] op_sel_hi:[0,1,0]
	v_fma_mix_f32 v57, v6, v38, v180 op_sel_hi:[0,1,0]
	v_fma_mix_f32 v57, v7, v38, v57 op_sel:[0,1,0] op_sel_hi:[0,1,0]
	v_add_f32_dpp v12, v12, v12 row_ror:1 row_mask:0xf bank_mask:0xf bound_ctrl:1
	v_fma_mix_f32 v57, v8, v39, v57 op_sel_hi:[0,1,0]
	v_fma_mix_f32 v57, v9, v39, v57 op_sel:[0,1,0] op_sel_hi:[0,1,0]
	v_add_f32_dpp v12, v12, v12 row_ror:2 row_mask:0xf bank_mask:0xf bound_ctrl:1
	v_pk_fma_f32 v[48:49], v[96:97], v[72:73], v[6:7] op_sel_hi:[1,0,1]
	v_pk_fma_f32 v[50:51], v[98:99], v[72:73], v[8:9] op_sel_hi:[1,0,1]
	v_add_f32_dpp v12, v12, v12 row_ror:4 row_mask:0xf bank_mask:0xf bound_ctrl:1
	v_add_f32_dpp v134, v134, v134 row_ror:4 row_mask:0xf bank_mask:0xa
	v_add_f32_dpp v134, v130, v130 row_ror:12 row_mask:0xf bank_mask:0x5
	v_add_f32_dpp v135, v135, v135 row_ror:4 row_mask:0xf bank_mask:0xa
	v_add_f32_dpp v12, v12, v12 row_ror:8 row_mask:0xf bank_mask:0xf bound_ctrl:1
	v_pk_fma_f32 v[6:7], v[92:93], v[12:13], v[48:49] op_sel_hi:[1,0,1] neg_lo:[1,0,0] neg_hi:[1,0,0]
	v_pk_fma_f32 v[8:9], v[94:95], v[12:13], v[50:51] op_sel_hi:[1,0,1] neg_lo:[1,0,0] neg_hi:[1,0,0]
	ds_read_b128 v[20:23], v10 offset:8448
	ds_read_b128 v[28:31], v10 offset:8960
	ds_read_b128 v[24:27], v10 offset:8704
	s_waitcnt lgkmcnt(4)
	s_nop 0
	v_fma_mix_f32 v12, v6, v110, v180 op_sel_hi:[0,1,0]
	v_fma_mix_f32 v12, v7, v110, v12 op_sel:[0,1,0] op_sel_hi:[0,1,0]
	v_fma_mix_f32 v12, v8, v111, v12 op_sel_hi:[0,1,0]
	v_fma_mix_f32 v12, v9, v111, v12 op_sel:[0,1,0] op_sel_hi:[0,1,0]
	v_fma_mix_f32 v81, v6, v90, v180 op_sel_hi:[0,1,0]
	v_fma_mix_f32 v81, v7, v90, v81 op_sel:[0,1,0] op_sel_hi:[0,1,0]
	v_add_f32_dpp v12, v12, v12 row_ror:1 row_mask:0xf bank_mask:0xf bound_ctrl:1
	v_fma_mix_f32 v81, v8, v91, v81 op_sel_hi:[0,1,0]
	v_fma_mix_f32 v81, v9, v91, v81 op_sel:[0,1,0] op_sel_hi:[0,1,0]
	v_add_f32_dpp v12, v12, v12 row_ror:2 row_mask:0xf bank_mask:0xf bound_ctrl:1
	v_pk_fma_f32 v[48:49], v[118:119], v[72:73], v[6:7] op_sel:[0,1,0]
	v_pk_fma_f32 v[50:51], v[120:121], v[72:73], v[8:9] op_sel:[0,1,0]
	v_add_f32_dpp v12, v12, v12 row_ror:4 row_mask:0xf bank_mask:0xf bound_ctrl:1
	v_add_f32_dpp v135, v131, v131 row_ror:12 row_mask:0xf bank_mask:0x5
	v_add_f32_dpp v136, v136, v136 row_ror:4 row_mask:0xf bank_mask:0xa
	v_add_f32_dpp v136, v132, v132 row_ror:12 row_mask:0xf bank_mask:0x5
	v_add_f32_dpp v12, v12, v12 row_ror:8 row_mask:0xf bank_mask:0xf bound_ctrl:1
	v_pk_fma_f32 v[6:7], v[114:115], v[12:13], v[48:49] op_sel_hi:[1,0,1] neg_lo:[1,0,0] neg_hi:[1,0,0]
	v_pk_fma_f32 v[8:9], v[116:117], v[12:13], v[50:51] op_sel_hi:[1,0,1] neg_lo:[1,0,0] neg_hi:[1,0,0]
	v_pk_mul_f32 v[6:7], v[6:7], v[106:107]
	v_pk_mul_f32 v[8:9], v[8:9], v[108:109]
	ds_read_b128 v[36:39], v10 offset:9472
	ds_read_b128 v[44:47], v10 offset:9984
	ds_read_b128 v[40:43], v10 offset:9728
	s_waitcnt lgkmcnt(3)
	s_nop 0
	v_fma_mix_f32 v12, v6, v20, v180 op_sel_hi:[0,1,0]
	v_fma_mix_f32 v12, v7, v20, v12 op_sel:[0,1,0] op_sel_hi:[0,1,0]
	v_fma_mix_f32 v12, v8, v21, v12 op_sel_hi:[0,1,0]
	v_fma_mix_f32 v12, v9, v21, v12 op_sel:[0,1,0] op_sel_hi:[0,1,0]
	v_fma_mix_f32 v82, v6, v112, v180 op_sel_hi:[0,1,0]
	v_fma_mix_f32 v82, v7, v112, v82 op_sel:[0,1,0] op_sel_hi:[0,1,0]
	v_add_f32_dpp v12, v12, v12 row_ror:1 row_mask:0xf bank_mask:0xf bound_ctrl:1
	v_fma_mix_f32 v82, v8, v113, v82 op_sel_hi:[0,1,0]
	v_fma_mix_f32 v82, v9, v113, v82 op_sel:[0,1,0] op_sel_hi:[0,1,0]
	v_add_f32_dpp v12, v12, v12 row_ror:2 row_mask:0xf bank_mask:0xf bound_ctrl:1
	v_pk_fma_f32 v[48:49], v[28:29], v[66:67], v[6:7] op_sel_hi:[1,0,1]
	v_pk_fma_f32 v[50:51], v[30:31], v[66:67], v[8:9] op_sel_hi:[1,0,1]
	v_add_f32_dpp v12, v12, v12 row_ror:4 row_mask:0xf bank_mask:0xf bound_ctrl:1
	v_add_f32_dpp v137, v137, v137 row_ror:4 row_mask:0xf bank_mask:0xa
	v_add_f32_dpp v137, v133, v133 row_ror:12 row_mask:0xf bank_mask:0x5
	v_add_f32_dpp v12, v12, v12 row_ror:8 row_mask:0xf bank_mask:0xf bound_ctrl:1
	v_pk_fma_f32 v[6:7], v[24:25], v[12:13], v[48:49] op_sel_hi:[1,0,1] neg_lo:[1,0,0] neg_hi:[1,0,0]
	v_pk_fma_f32 v[8:9], v[26:27], v[12:13], v[50:51] op_sel_hi:[1,0,1] neg_lo:[1,0,0] neg_hi:[1,0,0]
	ds_read_b128 v[88:91], v10 offset:10496
	ds_read_b128 v[96:99], v10 offset:11008
	ds_read_b128 v[92:95], v10 offset:10752
	s_waitcnt lgkmcnt(3)
	s_nop 0
	v_fma_mix_f32 v12, v6, v36, v180 op_sel_hi:[0,1,0]
	v_fma_mix_f32 v12, v7, v36, v12 op_sel:[0,1,0] op_sel_hi:[0,1,0]
	v_fma_mix_f32 v12, v8, v37, v12 op_sel_hi:[0,1,0]
	v_fma_mix_f32 v12, v9, v37, v12 op_sel:[0,1,0] op_sel_hi:[0,1,0]
	v_fma_mix_f32 v83, v6, v22, v180 op_sel_hi:[0,1,0]
	v_fma_mix_f32 v83, v7, v22, v83 op_sel:[0,1,0] op_sel_hi:[0,1,0]
	v_add_f32_dpp v12, v12, v12 row_ror:1 row_mask:0xf bank_mask:0xf bound_ctrl:1
	v_fma_mix_f32 v83, v8, v23, v83 op_sel_hi:[0,1,0]
	v_fma_mix_f32 v83, v9, v23, v83 op_sel:[0,1,0] op_sel_hi:[0,1,0]
	v_add_f32_dpp v12, v12, v12 row_ror:2 row_mask:0xf bank_mask:0xf bound_ctrl:1
	v_pk_fma_f32 v[48:49], v[44:45], v[66:67], v[6:7] op_sel:[0,1,0]
	v_pk_fma_f32 v[50:51], v[46:47], v[66:67], v[8:9] op_sel:[0,1,0]
	v_add_f32_dpp v12, v12, v12 row_ror:4 row_mask:0xf bank_mask:0xf bound_ctrl:1
	v_cndmask_b32_e64 v62, v136, v134, s[38:39]
	v_cndmask_b32_e64 v63, v134, v136, s[38:39]
	v_add_f32_dpp v12, v12, v12 row_ror:8 row_mask:0xf bank_mask:0xf bound_ctrl:1
	v_pk_fma_f32 v[6:7], v[40:41], v[12:13], v[48:49] op_sel_hi:[1,0,1] neg_lo:[1,0,0] neg_hi:[1,0,0]
	v_pk_fma_f32 v[8:9], v[42:43], v[12:13], v[50:51] op_sel_hi:[1,0,1] neg_lo:[1,0,0] neg_hi:[1,0,0]
	ds_read_b128 v[110:113], v10 offset:11520
	ds_read_b128 v[106:109], v10 offset:11264
	ds_read_b128 v[118:121], v10 offset:12032
	ds_read_b128 v[114:117], v10 offset:11776
	ds_read_b128 v[70:73], v11 offset:768
	s_waitcnt lgkmcnt(5)
	s_nop 0
	v_fma_mix_f32 v12, v6, v88, v180 op_sel_hi:[0,1,0]
	v_fma_mix_f32 v12, v7, v88, v12 op_sel:[0,1,0] op_sel_hi:[0,1,0]
	v_fma_mix_f32 v12, v8, v89, v12 op_sel_hi:[0,1,0]
	v_fma_mix_f32 v12, v9, v89, v12 op_sel:[0,1,0] op_sel_hi:[0,1,0]
	v_fma_mix_f32 v100, v6, v38, v180 op_sel_hi:[0,1,0]
	v_fma_mix_f32 v100, v7, v38, v100 op_sel:[0,1,0] op_sel_hi:[0,1,0]
	v_add_f32_dpp v12, v12, v12 row_ror:1 row_mask:0xf bank_mask:0xf bound_ctrl:1
	v_fma_mix_f32 v100, v8, v39, v100 op_sel_hi:[0,1,0]
	v_fma_mix_f32 v100, v9, v39, v100 op_sel:[0,1,0] op_sel_hi:[0,1,0]
	v_add_f32_dpp v12, v12, v12 row_ror:2 row_mask:0xf bank_mask:0xf bound_ctrl:1
	v_pk_fma_f32 v[48:49], v[96:97], v[68:69], v[6:7] op_sel_hi:[1,0,1]
	v_pk_fma_f32 v[50:51], v[98:99], v[68:69], v[8:9] op_sel_hi:[1,0,1]
	v_add_f32_dpp v12, v12, v12 row_ror:4 row_mask:0xf bank_mask:0xf bound_ctrl:1
	v_cndmask_b32_e64 v64, v137, v135, s[38:39]
	v_cndmask_b32_e64 v65, v135, v137, s[38:39]
	v_add_f32_dpp v12, v12, v12 row_ror:8 row_mask:0xf bank_mask:0xf bound_ctrl:1
	v_pk_fma_f32 v[6:7], v[92:93], v[12:13], v[48:49] op_sel_hi:[1,0,1] neg_lo:[1,0,0] neg_hi:[1,0,0]
	v_pk_fma_f32 v[8:9], v[94:95], v[12:13], v[50:51] op_sel_hi:[1,0,1] neg_lo:[1,0,0] neg_hi:[1,0,0]
	ds_read_b128 v[20:23], v10 offset:12544
	ds_read_b128 v[28:31], v10 offset:13056
	ds_read_b128 v[24:27], v10 offset:12800
	s_waitcnt lgkmcnt(4)
	s_nop 0
	v_fma_mix_f32 v12, v6, v110, v180 op_sel_hi:[0,1,0]
	v_fma_mix_f32 v12, v7, v110, v12 op_sel:[0,1,0] op_sel_hi:[0,1,0]
	v_fma_mix_f32 v12, v8, v111, v12 op_sel_hi:[0,1,0]
	v_fma_mix_f32 v12, v9, v111, v12 op_sel:[0,1,0] op_sel_hi:[0,1,0]
	v_fma_mix_f32 v101, v6, v90, v180 op_sel_hi:[0,1,0]
	v_fma_mix_f32 v101, v7, v90, v101 op_sel:[0,1,0] op_sel_hi:[0,1,0]
	v_add_f32_dpp v12, v12, v12 row_ror:1 row_mask:0xf bank_mask:0xf bound_ctrl:1
	v_fma_mix_f32 v101, v8, v91, v101 op_sel_hi:[0,1,0]
	v_fma_mix_f32 v101, v9, v91, v101 op_sel:[0,1,0] op_sel_hi:[0,1,0]
	v_add_f32_dpp v12, v12, v12 row_ror:2 row_mask:0xf bank_mask:0xf bound_ctrl:1
	v_pk_fma_f32 v[48:49], v[118:119], v[68:69], v[6:7] op_sel:[0,1,0]
	v_pk_fma_f32 v[50:51], v[120:121], v[68:69], v[8:9] op_sel:[0,1,0]
	v_add_f32_dpp v12, v12, v12 row_ror:4 row_mask:0xf bank_mask:0xf bound_ctrl:1
	v_add_f32_dpp v62, v63, v62 quad_perm:[2,3,0,1] row_mask:0xf bank_mask:0xf bound_ctrl:1
	v_add_f32_dpp v63, v65, v64 quad_perm:[2,3,0,1] row_mask:0xf bank_mask:0xf bound_ctrl:1
	v_add_f32_dpp v12, v12, v12 row_ror:8 row_mask:0xf bank_mask:0xf bound_ctrl:1
	v_pk_fma_f32 v[6:7], v[114:115], v[12:13], v[48:49] op_sel_hi:[1,0,1] neg_lo:[1,0,0] neg_hi:[1,0,0]
	v_pk_fma_f32 v[8:9], v[116:117], v[12:13], v[50:51] op_sel_hi:[1,0,1] neg_lo:[1,0,0] neg_hi:[1,0,0]
	v_pk_mul_f32 v[6:7], v[6:7], v[106:107]
	v_pk_mul_f32 v[8:9], v[8:9], v[108:109]
	ds_read_b128 v[36:39], v10 offset:13568
	ds_read_b128 v[44:47], v10 offset:14080
	ds_read_b128 v[40:43], v10 offset:13824
	s_waitcnt lgkmcnt(3)
	s_nop 0
	v_fma_mix_f32 v12, v6, v20, v180 op_sel_hi:[0,1,0]
	v_fma_mix_f32 v12, v7, v20, v12 op_sel:[0,1,0] op_sel_hi:[0,1,0]
	v_fma_mix_f32 v12, v8, v21, v12 op_sel_hi:[0,1,0]
	v_fma_mix_f32 v12, v9, v21, v12 op_sel:[0,1,0] op_sel_hi:[0,1,0]
	v_fma_mix_f32 v102, v6, v112, v180 op_sel_hi:[0,1,0]
	v_fma_mix_f32 v102, v7, v112, v102 op_sel:[0,1,0] op_sel_hi:[0,1,0]
	v_add_f32_dpp v12, v12, v12 row_ror:1 row_mask:0xf bank_mask:0xf bound_ctrl:1
	v_fma_mix_f32 v102, v8, v113, v102 op_sel_hi:[0,1,0]
	v_fma_mix_f32 v102, v9, v113, v102 op_sel:[0,1,0] op_sel_hi:[0,1,0]
	v_add_f32_dpp v12, v12, v12 row_ror:2 row_mask:0xf bank_mask:0xf bound_ctrl:1
	v_pk_fma_f32 v[48:49], v[28:29], v[70:71], v[6:7] op_sel_hi:[1,0,1]
	v_pk_fma_f32 v[50:51], v[30:31], v[70:71], v[8:9] op_sel_hi:[1,0,1]
	v_add_f32_dpp v12, v12, v12 row_ror:4 row_mask:0xf bank_mask:0xf bound_ctrl:1
	v_cndmask_b32_e64 v65, v63, v62, s[40:41]
	v_cndmask_b32_e64 v62, v62, v63, s[40:41]
	v_add_f32_dpp v12, v12, v12 row_ror:8 row_mask:0xf bank_mask:0xf bound_ctrl:1
	v_pk_fma_f32 v[6:7], v[24:25], v[12:13], v[48:49] op_sel_hi:[1,0,1] neg_lo:[1,0,0] neg_hi:[1,0,0]
	v_pk_fma_f32 v[8:9], v[26:27], v[12:13], v[50:51] op_sel_hi:[1,0,1] neg_lo:[1,0,0] neg_hi:[1,0,0]
	ds_read_b128 v[88:91], v10 offset:14592
	ds_read_b128 v[96:99], v10 offset:15104
	ds_read_b128 v[92:95], v10 offset:14848
	s_waitcnt lgkmcnt(3)
	s_nop 0
	v_fma_mix_f32 v12, v6, v36, v180 op_sel_hi:[0,1,0]
	v_fma_mix_f32 v12, v7, v36, v12 op_sel:[0,1,0] op_sel_hi:[0,1,0]
	v_fma_mix_f32 v12, v8, v37, v12 op_sel_hi:[0,1,0]
	v_fma_mix_f32 v12, v9, v37, v12 op_sel:[0,1,0] op_sel_hi:[0,1,0]
	v_fma_mix_f32 v103, v6, v22, v180 op_sel_hi:[0,1,0]
	v_fma_mix_f32 v103, v7, v22, v103 op_sel:[0,1,0] op_sel_hi:[0,1,0]
	v_add_f32_dpp v12, v12, v12 row_ror:1 row_mask:0xf bank_mask:0xf bound_ctrl:1
	v_fma_mix_f32 v103, v8, v23, v103 op_sel_hi:[0,1,0]
	v_fma_mix_f32 v103, v9, v23, v103 op_sel:[0,1,0] op_sel_hi:[0,1,0]
	v_add_f32_dpp v12, v12, v12 row_ror:2 row_mask:0xf bank_mask:0xf bound_ctrl:1
	v_pk_fma_f32 v[48:49], v[44:45], v[70:71], v[6:7] op_sel:[0,1,0]
	v_pk_fma_f32 v[50:51], v[46:47], v[70:71], v[8:9] op_sel:[0,1,0]
	v_add_f32_dpp v12, v12, v12 row_ror:4 row_mask:0xf bank_mask:0xf bound_ctrl:1
	v_add_f32_dpp v62, v62, v65 quad_perm:[1,0,3,2] row_mask:0xf bank_mask:0xf bound_ctrl:1
	v_cvt_pk_bf16_f32 v62, v62, v62
	v_add_f32_dpp v12, v12, v12 row_ror:8 row_mask:0xf bank_mask:0xf bound_ctrl:1
	v_pk_fma_f32 v[6:7], v[40:41], v[12:13], v[48:49] op_sel_hi:[1,0,1] neg_lo:[1,0,0] neg_hi:[1,0,0]
	v_pk_fma_f32 v[8:9], v[42:43], v[12:13], v[50:51] op_sel_hi:[1,0,1] neg_lo:[1,0,0] neg_hi:[1,0,0]
	ds_read_b128 v[110:113], v10 offset:15616
	ds_read_b128 v[106:109], v10 offset:15360
	ds_read_b128 v[118:121], v10 offset:16128
	ds_read_b128 v[114:117], v10 offset:15872
	ds_read_b128 v[66:69], v11 offset:1024
	s_waitcnt lgkmcnt(5)
	s_nop 0
	v_fma_mix_f32 v12, v6, v88, v180 op_sel_hi:[0,1,0]
	v_fma_mix_f32 v12, v7, v88, v12 op_sel:[0,1,0] op_sel_hi:[0,1,0]
	v_fma_mix_f32 v12, v8, v89, v12 op_sel_hi:[0,1,0]
	v_fma_mix_f32 v12, v9, v89, v12 op_sel:[0,1,0] op_sel_hi:[0,1,0]
	v_fma_mix_f32 v104, v6, v38, v180 op_sel_hi:[0,1,0]
	v_fma_mix_f32 v104, v7, v38, v104 op_sel:[0,1,0] op_sel_hi:[0,1,0]
	v_add_f32_dpp v12, v12, v12 row_ror:1 row_mask:0xf bank_mask:0xf bound_ctrl:1
	v_fma_mix_f32 v104, v8, v39, v104 op_sel_hi:[0,1,0]
	v_fma_mix_f32 v104, v9, v39, v104 op_sel:[0,1,0] op_sel_hi:[0,1,0]
	v_add_f32_dpp v12, v12, v12 row_ror:2 row_mask:0xf bank_mask:0xf bound_ctrl:1
	v_pk_fma_f32 v[48:49], v[96:97], v[72:73], v[6:7] op_sel_hi:[1,0,1]
	v_pk_fma_f32 v[50:51], v[98:99], v[72:73], v[8:9] op_sel_hi:[1,0,1]
	v_add_f32_dpp v12, v12, v12 row_ror:4 row_mask:0xf bank_mask:0xf bound_ctrl:1
	s_mov_b64 exec, s[100:101]
	s_nop 0
	global_store_short v[170:171], v62, off
	s_mov_b64 exec, -1
	s_nop 0
	v_add_f32_dpp v12, v12, v12 row_ror:8 row_mask:0xf bank_mask:0xf bound_ctrl:1
	v_pk_fma_f32 v[6:7], v[92:93], v[12:13], v[48:49] op_sel_hi:[1,0,1] neg_lo:[1,0,0] neg_hi:[1,0,0]
	v_pk_fma_f32 v[8:9], v[94:95], v[12:13], v[50:51] op_sel_hi:[1,0,1] neg_lo:[1,0,0] neg_hi:[1,0,0]
	ds_read_b128 v[20:23], v10 offset:16640
	ds_read_b128 v[28:31], v10 offset:17152
	ds_read_b128 v[24:27], v10 offset:16896
	s_waitcnt lgkmcnt(4)
	s_nop 0
	v_fma_mix_f32 v12, v6, v110, v180 op_sel_hi:[0,1,0]
	v_fma_mix_f32 v12, v7, v110, v12 op_sel:[0,1,0] op_sel_hi:[0,1,0]
	v_fma_mix_f32 v12, v8, v111, v12 op_sel_hi:[0,1,0]
	v_fma_mix_f32 v12, v9, v111, v12 op_sel:[0,1,0] op_sel_hi:[0,1,0]
	v_fma_mix_f32 v105, v6, v90, v180 op_sel_hi:[0,1,0]
	v_fma_mix_f32 v105, v7, v90, v105 op_sel:[0,1,0] op_sel_hi:[0,1,0]
	v_add_f32_dpp v12, v12, v12 row_ror:1 row_mask:0xf bank_mask:0xf bound_ctrl:1
	v_fma_mix_f32 v105, v8, v91, v105 op_sel_hi:[0,1,0]
	v_fma_mix_f32 v105, v9, v91, v105 op_sel:[0,1,0] op_sel_hi:[0,1,0]
	v_add_f32_dpp v12, v12, v12 row_ror:2 row_mask:0xf bank_mask:0xf bound_ctrl:1
	v_pk_fma_f32 v[48:49], v[118:119], v[72:73], v[6:7] op_sel:[0,1,0]
	v_pk_fma_f32 v[50:51], v[120:121], v[72:73], v[8:9] op_sel:[0,1,0]
	v_add_f32_dpp v12, v12, v12 row_ror:4 row_mask:0xf bank_mask:0xf bound_ctrl:1
	s_nop 1
	s_nop 0
	v_add_f32_dpp v12, v12, v12 row_ror:8 row_mask:0xf bank_mask:0xf bound_ctrl:1
	v_pk_fma_f32 v[6:7], v[114:115], v[12:13], v[48:49] op_sel_hi:[1,0,1] neg_lo:[1,0,0] neg_hi:[1,0,0]
	v_pk_fma_f32 v[8:9], v[116:117], v[12:13], v[50:51] op_sel_hi:[1,0,1] neg_lo:[1,0,0] neg_hi:[1,0,0]
	v_pk_mul_f32 v[6:7], v[6:7], v[106:107]
	v_pk_mul_f32 v[8:9], v[8:9], v[108:109]
	ds_read_b128 v[36:39], v10 offset:17664
	ds_read_b128 v[44:47], v10 offset:18176
	ds_read_b128 v[40:43], v10 offset:17920
	s_waitcnt lgkmcnt(3)
	s_nop 0
	v_fma_mix_f32 v12, v6, v20, v180 op_sel_hi:[0,1,0]
	v_fma_mix_f32 v12, v7, v20, v12 op_sel:[0,1,0] op_sel_hi:[0,1,0]
	v_fma_mix_f32 v12, v8, v21, v12 op_sel_hi:[0,1,0]
	v_fma_mix_f32 v12, v9, v21, v12 op_sel:[0,1,0] op_sel_hi:[0,1,0]
	v_fma_mix_f32 v61, v6, v112, v180 op_sel_hi:[0,1,0]
	v_fma_mix_f32 v61, v7, v112, v61 op_sel:[0,1,0] op_sel_hi:[0,1,0]
	v_add_f32_dpp v12, v12, v12 row_ror:1 row_mask:0xf bank_mask:0xf bound_ctrl:1
	v_fma_mix_f32 v61, v8, v113, v61 op_sel_hi:[0,1,0]
	v_fma_mix_f32 v61, v9, v113, v61 op_sel:[0,1,0] op_sel_hi:[0,1,0]
	v_add_f32_dpp v12, v12, v12 row_ror:2 row_mask:0xf bank_mask:0xf bound_ctrl:1
	v_pk_fma_f32 v[48:49], v[28:29], v[66:67], v[6:7] op_sel_hi:[1,0,1]
	v_pk_fma_f32 v[50:51], v[30:31], v[66:67], v[8:9] op_sel_hi:[1,0,1]
	v_add_f32_dpp v12, v12, v12 row_ror:4 row_mask:0xf bank_mask:0xf bound_ctrl:1
	s_nop 1
	s_nop 0
	v_add_f32_dpp v12, v12, v12 row_ror:8 row_mask:0xf bank_mask:0xf bound_ctrl:1
	v_pk_fma_f32 v[6:7], v[24:25], v[12:13], v[48:49] op_sel_hi:[1,0,1] neg_lo:[1,0,0] neg_hi:[1,0,0]
	v_pk_fma_f32 v[8:9], v[26:27], v[12:13], v[50:51] op_sel_hi:[1,0,1] neg_lo:[1,0,0] neg_hi:[1,0,0]
	ds_read_b128 v[88:91], v10 offset:18688
	ds_read_b128 v[96:99], v10 offset:19200
	ds_read_b128 v[92:95], v10 offset:18944
	s_waitcnt lgkmcnt(3)
	s_nop 0
	v_fma_mix_f32 v12, v6, v36, v180 op_sel_hi:[0,1,0]
	v_fma_mix_f32 v12, v7, v36, v12 op_sel:[0,1,0] op_sel_hi:[0,1,0]
	v_fma_mix_f32 v12, v8, v37, v12 op_sel_hi:[0,1,0]
	v_fma_mix_f32 v12, v9, v37, v12 op_sel:[0,1,0] op_sel_hi:[0,1,0]
	v_fma_mix_f32 v122, v6, v22, v180 op_sel_hi:[0,1,0]
	v_fma_mix_f32 v122, v7, v22, v122 op_sel:[0,1,0] op_sel_hi:[0,1,0]
	v_add_f32_dpp v12, v12, v12 row_ror:1 row_mask:0xf bank_mask:0xf bound_ctrl:1
	v_fma_mix_f32 v122, v8, v23, v122 op_sel_hi:[0,1,0]
	v_fma_mix_f32 v122, v9, v23, v122 op_sel:[0,1,0] op_sel_hi:[0,1,0]
	v_add_f32_dpp v12, v12, v12 row_ror:2 row_mask:0xf bank_mask:0xf bound_ctrl:1
	v_pk_fma_f32 v[48:49], v[44:45], v[66:67], v[6:7] op_sel:[0,1,0]
	v_pk_fma_f32 v[50:51], v[46:47], v[66:67], v[8:9] op_sel:[0,1,0]
	v_add_f32_dpp v12, v12, v12 row_ror:4 row_mask:0xf bank_mask:0xf bound_ctrl:1
	v_add_f32_dpp v83, v83, v83 row_ror:8 row_mask:0xf bank_mask:0xc
	v_add_f32_dpp v83, v52, v52 row_ror:8 row_mask:0xf bank_mask:0x3
	v_add_f32_dpp v100, v100, v100 row_ror:8 row_mask:0xf bank_mask:0xc
	v_add_f32_dpp v12, v12, v12 row_ror:8 row_mask:0xf bank_mask:0xf bound_ctrl:1
	v_pk_fma_f32 v[6:7], v[40:41], v[12:13], v[48:49] op_sel_hi:[1,0,1] neg_lo:[1,0,0] neg_hi:[1,0,0]
	v_pk_fma_f32 v[8:9], v[42:43], v[12:13], v[50:51] op_sel_hi:[1,0,1] neg_lo:[1,0,0] neg_hi:[1,0,0]
	ds_read_b128 v[110:113], v10 offset:19712
	ds_read_b128 v[106:109], v10 offset:19456
	ds_read_b128 v[118:121], v10 offset:20224
	ds_read_b128 v[114:117], v10 offset:19968
	ds_read_b128 v[70:73], v11 offset:1280
	s_waitcnt lgkmcnt(5)
	s_nop 0
	v_fma_mix_f32 v12, v6, v88, v180 op_sel_hi:[0,1,0]
	v_fma_mix_f32 v12, v7, v88, v12 op_sel:[0,1,0] op_sel_hi:[0,1,0]
	v_fma_mix_f32 v12, v8, v89, v12 op_sel_hi:[0,1,0]
	v_fma_mix_f32 v12, v9, v89, v12 op_sel:[0,1,0] op_sel_hi:[0,1,0]
	v_fma_mix_f32 v123, v6, v38, v180 op_sel_hi:[0,1,0]
	v_fma_mix_f32 v123, v7, v38, v123 op_sel:[0,1,0] op_sel_hi:[0,1,0]
	v_add_f32_dpp v12, v12, v12 row_ror:1 row_mask:0xf bank_mask:0xf bound_ctrl:1
	v_fma_mix_f32 v123, v8, v39, v123 op_sel_hi:[0,1,0]
	v_fma_mix_f32 v123, v9, v39, v123 op_sel:[0,1,0] op_sel_hi:[0,1,0]
	v_add_f32_dpp v12, v12, v12 row_ror:2 row_mask:0xf bank_mask:0xf bound_ctrl:1
	v_pk_fma_f32 v[48:49], v[96:97], v[68:69], v[6:7] op_sel_hi:[1,0,1]
	v_pk_fma_f32 v[50:51], v[98:99], v[68:69], v[8:9] op_sel_hi:[1,0,1]
	v_add_f32_dpp v12, v12, v12 row_ror:4 row_mask:0xf bank_mask:0xf bound_ctrl:1
	v_add_f32_dpp v100, v53, v53 row_ror:8 row_mask:0xf bank_mask:0x3
	v_add_f32_dpp v101, v101, v101 row_ror:8 row_mask:0xf bank_mask:0xc
	v_add_f32_dpp v101, v54, v54 row_ror:8 row_mask:0xf bank_mask:0x3
	v_add_f32_dpp v12, v12, v12 row_ror:8 row_mask:0xf bank_mask:0xf bound_ctrl:1
	v_pk_fma_f32 v[6:7], v[92:93], v[12:13], v[48:49] op_sel_hi:[1,0,1] neg_lo:[1,0,0] neg_hi:[1,0,0]
	v_pk_fma_f32 v[8:9], v[94:95], v[12:13], v[50:51] op_sel_hi:[1,0,1] neg_lo:[1,0,0] neg_hi:[1,0,0]
	ds_read_b128 v[20:23], v10 offset:20736
	ds_read_b128 v[28:31], v10 offset:21248
	ds_read_b128 v[24:27], v10 offset:20992
	s_waitcnt lgkmcnt(4)
	s_nop 0
	v_fma_mix_f32 v12, v6, v110, v180 op_sel_hi:[0,1,0]
	v_fma_mix_f32 v12, v7, v110, v12 op_sel:[0,1,0] op_sel_hi:[0,1,0]
	v_fma_mix_f32 v12, v8, v111, v12 op_sel_hi:[0,1,0]
	v_fma_mix_f32 v12, v9, v111, v12 op_sel:[0,1,0] op_sel_hi:[0,1,0]
	v_fma_mix_f32 v124, v6, v90, v180 op_sel_hi:[0,1,0]
	v_fma_mix_f32 v124, v7, v90, v124 op_sel:[0,1,0] op_sel_hi:[0,1,0]
	v_add_f32_dpp v12, v12, v12 row_ror:1 row_mask:0xf bank_mask:0xf bound_ctrl:1
	v_fma_mix_f32 v124, v8, v91, v124 op_sel_hi:[0,1,0]
	v_fma_mix_f32 v124, v9, v91, v124 op_sel:[0,1,0] op_sel_hi:[0,1,0]
	v_add_f32_dpp v12, v12, v12 row_ror:2 row_mask:0xf bank_mask:0xf bound_ctrl:1
	v_pk_fma_f32 v[48:49], v[118:119], v[68:69], v[6:7] op_sel:[0,1,0]
	v_pk_fma_f32 v[50:51], v[120:121], v[68:69], v[8:9] op_sel:[0,1,0]
	v_add_f32_dpp v12, v12, v12 row_ror:4 row_mask:0xf bank_mask:0xf bound_ctrl:1
	v_add_f32_dpp v102, v102, v102 row_ror:8 row_mask:0xf bank_mask:0xc
	v_add_f32_dpp v102, v55, v55 row_ror:8 row_mask:0xf bank_mask:0x3
	v_add_f32_dpp v103, v103, v103 row_ror:8 row_mask:0xf bank_mask:0xc
	v_add_f32_dpp v12, v12, v12 row_ror:8 row_mask:0xf bank_mask:0xf bound_ctrl:1
	v_pk_fma_f32 v[6:7], v[114:115], v[12:13], v[48:49] op_sel_hi:[1,0,1] neg_lo:[1,0,0] neg_hi:[1,0,0]
	v_pk_fma_f32 v[8:9], v[116:117], v[12:13], v[50:51] op_sel_hi:[1,0,1] neg_lo:[1,0,0] neg_hi:[1,0,0]
	v_pk_mul_f32 v[6:7], v[6:7], v[106:107]
	v_pk_mul_f32 v[8:9], v[8:9], v[108:109]
	ds_read_b128 v[36:39], v10 offset:21760
	ds_read_b128 v[44:47], v10 offset:22272
	ds_read_b128 v[40:43], v10 offset:22016
	s_waitcnt lgkmcnt(3)
	s_nop 0
	v_fma_mix_f32 v12, v6, v20, v180 op_sel_hi:[0,1,0]
	v_fma_mix_f32 v12, v7, v20, v12 op_sel:[0,1,0] op_sel_hi:[0,1,0]
	v_fma_mix_f32 v12, v8, v21, v12 op_sel_hi:[0,1,0]
	v_fma_mix_f32 v12, v9, v21, v12 op_sel:[0,1,0] op_sel_hi:[0,1,0]
	v_fma_mix_f32 v125, v6, v112, v180 op_sel_hi:[0,1,0]
	v_fma_mix_f32 v125, v7, v112, v125 op_sel:[0,1,0] op_sel_hi:[0,1,0]
	v_add_f32_dpp v12, v12, v12 row_ror:1 row_mask:0xf bank_mask:0xf bound_ctrl:1
	v_fma_mix_f32 v125, v8, v113, v125 op_sel_hi:[0,1,0]
	v_fma_mix_f32 v125, v9, v113, v125 op_sel:[0,1,0] op_sel_hi:[0,1,0]
	v_add_f32_dpp v12, v12, v12 row_ror:2 row_mask:0xf bank_mask:0xf bound_ctrl:1
	v_pk_fma_f32 v[48:49], v[28:29], v[70:71], v[6:7] op_sel_hi:[1,0,1]
	v_pk_fma_f32 v[50:51], v[30:31], v[70:71], v[8:9] op_sel_hi:[1,0,1]
	v_add_f32_dpp v12, v12, v12 row_ror:4 row_mask:0xf bank_mask:0xf bound_ctrl:1
	v_add_f32_dpp v103, v56, v56 row_ror:8 row_mask:0xf bank_mask:0x3
	v_add_f32_dpp v104, v104, v104 row_ror:8 row_mask:0xf bank_mask:0xc
	v_add_f32_dpp v104, v57, v57 row_ror:8 row_mask:0xf bank_mask:0x3
	v_add_f32_dpp v12, v12, v12 row_ror:8 row_mask:0xf bank_mask:0xf bound_ctrl:1
	v_pk_fma_f32 v[6:7], v[24:25], v[12:13], v[48:49] op_sel_hi:[1,0,1] neg_lo:[1,0,0] neg_hi:[1,0,0]
	v_pk_fma_f32 v[8:9], v[26:27], v[12:13], v[50:51] op_sel_hi:[1,0,1] neg_lo:[1,0,0] neg_hi:[1,0,0]
	ds_read_b128 v[88:91], v10 offset:22784
	ds_read_b128 v[96:99], v10 offset:23296
	ds_read_b128 v[92:95], v10 offset:23040
	s_waitcnt lgkmcnt(3)
	s_nop 0
	v_fma_mix_f32 v12, v6, v36, v180 op_sel_hi:[0,1,0]
	v_fma_mix_f32 v12, v7, v36, v12 op_sel:[0,1,0] op_sel_hi:[0,1,0]
	v_fma_mix_f32 v12, v8, v37, v12 op_sel_hi:[0,1,0]
	v_fma_mix_f32 v12, v9, v37, v12 op_sel:[0,1,0] op_sel_hi:[0,1,0]
	v_fma_mix_f32 v126, v6, v22, v180 op_sel_hi:[0,1,0]
	v_fma_mix_f32 v126, v7, v22, v126 op_sel:[0,1,0] op_sel_hi:[0,1,0]
	v_add_f32_dpp v12, v12, v12 row_ror:1 row_mask:0xf bank_mask:0xf bound_ctrl:1
	v_fma_mix_f32 v126, v8, v23, v126 op_sel_hi:[0,1,0]
	v_fma_mix_f32 v126, v9, v23, v126 op_sel:[0,1,0] op_sel_hi:[0,1,0]
	v_add_f32_dpp v12, v12, v12 row_ror:2 row_mask:0xf bank_mask:0xf bound_ctrl:1
	v_pk_fma_f32 v[48:49], v[44:45], v[70:71], v[6:7] op_sel:[0,1,0]
	v_pk_fma_f32 v[50:51], v[46:47], v[70:71], v[8:9] op_sel:[0,1,0]
	v_add_f32_dpp v12, v12, v12 row_ror:4 row_mask:0xf bank_mask:0xf bound_ctrl:1
	v_add_f32_dpp v105, v105, v105 row_ror:8 row_mask:0xf bank_mask:0xc
	v_add_f32_dpp v105, v81, v81 row_ror:8 row_mask:0xf bank_mask:0x3
	v_add_f32_dpp v12, v12, v12 row_ror:8 row_mask:0xf bank_mask:0xf bound_ctrl:1
	v_pk_fma_f32 v[6:7], v[40:41], v[12:13], v[48:49] op_sel_hi:[1,0,1] neg_lo:[1,0,0] neg_hi:[1,0,0]
	v_pk_fma_f32 v[8:9], v[42:43], v[12:13], v[50:51] op_sel_hi:[1,0,1] neg_lo:[1,0,0] neg_hi:[1,0,0]
	ds_read_b128 v[110:113], v10 offset:23808
	ds_read_b128 v[106:109], v10 offset:23552
	ds_read_b128 v[118:121], v10 offset:24320
	ds_read_b128 v[114:117], v10 offset:24064
	ds_read_b128 v[66:69], v11 offset:1536
	s_waitcnt lgkmcnt(5)
	s_nop 0
	v_fma_mix_f32 v12, v6, v88, v180 op_sel_hi:[0,1,0]
	v_fma_mix_f32 v12, v7, v88, v12 op_sel:[0,1,0] op_sel_hi:[0,1,0]
	v_fma_mix_f32 v12, v8, v89, v12 op_sel_hi:[0,1,0]
	v_fma_mix_f32 v12, v9, v89, v12 op_sel:[0,1,0] op_sel_hi:[0,1,0]
	v_fma_mix_f32 v127, v6, v38, v180 op_sel_hi:[0,1,0]
	v_fma_mix_f32 v127, v7, v38, v127 op_sel:[0,1,0] op_sel_hi:[0,1,0]
	v_add_f32_dpp v12, v12, v12 row_ror:1 row_mask:0xf bank_mask:0xf bound_ctrl:1
	v_fma_mix_f32 v127, v8, v39, v127 op_sel_hi:[0,1,0]
	v_fma_mix_f32 v127, v9, v39, v127 op_sel:[0,1,0] op_sel_hi:[0,1,0]
	v_add_f32_dpp v12, v12, v12 row_ror:2 row_mask:0xf bank_mask:0xf bound_ctrl:1
	v_pk_fma_f32 v[48:49], v[96:97], v[72:73], v[6:7] op_sel_hi:[1,0,1]
	v_pk_fma_f32 v[50:51], v[98:99], v[72:73], v[8:9] op_sel_hi:[1,0,1]
	v_add_f32_dpp v12, v12, v12 row_ror:4 row_mask:0xf bank_mask:0xf bound_ctrl:1
	v_add_f32_dpp v61, v61, v61 row_ror:8 row_mask:0xf bank_mask:0xc
	v_add_f32_dpp v61, v82, v82 row_ror:8 row_mask:0xf bank_mask:0x3
	v_add_f32_dpp v12, v12, v12 row_ror:8 row_mask:0xf bank_mask:0xf bound_ctrl:1
	v_pk_fma_f32 v[6:7], v[92:93], v[12:13], v[48:49] op_sel_hi:[1,0,1] neg_lo:[1,0,0] neg_hi:[1,0,0]
	v_pk_fma_f32 v[8:9], v[94:95], v[12:13], v[50:51] op_sel_hi:[1,0,1] neg_lo:[1,0,0] neg_hi:[1,0,0]
	ds_read_b128 v[20:23], v10 offset:24832
	ds_read_b128 v[28:31], v10 offset:25344
	ds_read_b128 v[24:27], v10 offset:25088
	s_waitcnt lgkmcnt(4)
	s_nop 0
	v_fma_mix_f32 v12, v6, v110, v180 op_sel_hi:[0,1,0]
	v_fma_mix_f32 v12, v7, v110, v12 op_sel:[0,1,0] op_sel_hi:[0,1,0]
	v_fma_mix_f32 v12, v8, v111, v12 op_sel_hi:[0,1,0]
	v_fma_mix_f32 v12, v9, v111, v12 op_sel:[0,1,0] op_sel_hi:[0,1,0]
	v_fma_mix_f32 v128, v6, v90, v180 op_sel_hi:[0,1,0]
	v_fma_mix_f32 v128, v7, v90, v128 op_sel:[0,1,0] op_sel_hi:[0,1,0]
	v_add_f32_dpp v12, v12, v12 row_ror:1 row_mask:0xf bank_mask:0xf bound_ctrl:1
	v_fma_mix_f32 v128, v8, v91, v128 op_sel_hi:[0,1,0]
	v_fma_mix_f32 v128, v9, v91, v128 op_sel:[0,1,0] op_sel_hi:[0,1,0]
	v_add_f32_dpp v12, v12, v12 row_ror:2 row_mask:0xf bank_mask:0xf bound_ctrl:1
	v_pk_fma_f32 v[48:49], v[118:119], v[72:73], v[6:7] op_sel:[0,1,0]
	v_pk_fma_f32 v[50:51], v[120:121], v[72:73], v[8:9] op_sel:[0,1,0]
	v_add_f32_dpp v12, v12, v12 row_ror:4 row_mask:0xf bank_mask:0xf bound_ctrl:1
	v_add_f32_dpp v103, v103, v103 row_ror:4 row_mask:0xf bank_mask:0xa
	v_add_f32_dpp v103, v83, v83 row_ror:12 row_mask:0xf bank_mask:0x5
	v_add_f32_dpp v104, v104, v104 row_ror:4 row_mask:0xf bank_mask:0xa
	v_add_f32_dpp v12, v12, v12 row_ror:8 row_mask:0xf bank_mask:0xf bound_ctrl:1
	v_pk_fma_f32 v[6:7], v[114:115], v[12:13], v[48:49] op_sel_hi:[1,0,1] neg_lo:[1,0,0] neg_hi:[1,0,0]
	v_pk_fma_f32 v[8:9], v[116:117], v[12:13], v[50:51] op_sel_hi:[1,0,1] neg_lo:[1,0,0] neg_hi:[1,0,0]
	v_pk_mul_f32 v[6:7], v[6:7], v[106:107]
	v_pk_mul_f32 v[8:9], v[8:9], v[108:109]
	ds_read_b128 v[36:39], v10 offset:25856
	ds_read_b128 v[44:47], v10 offset:26368
	ds_read_b128 v[40:43], v10 offset:26112
	s_waitcnt lgkmcnt(3)
	s_nop 0
	v_fma_mix_f32 v12, v6, v20, v180 op_sel_hi:[0,1,0]
	v_fma_mix_f32 v12, v7, v20, v12 op_sel:[0,1,0] op_sel_hi:[0,1,0]
	v_fma_mix_f32 v12, v8, v21, v12 op_sel_hi:[0,1,0]
	v_fma_mix_f32 v12, v9, v21, v12 op_sel:[0,1,0] op_sel_hi:[0,1,0]
	v_fma_mix_f32 v129, v6, v112, v180 op_sel_hi:[0,1,0]
	v_fma_mix_f32 v129, v7, v112, v129 op_sel:[0,1,0] op_sel_hi:[0,1,0]
	v_add_f32_dpp v12, v12, v12 row_ror:1 row_mask:0xf bank_mask:0xf bound_ctrl:1
	v_fma_mix_f32 v129, v8, v113, v129 op_sel_hi:[0,1,0]
	v_fma_mix_f32 v129, v9, v113, v129 op_sel:[0,1,0] op_sel_hi:[0,1,0]
	v_add_f32_dpp v12, v12, v12 row_ror:2 row_mask:0xf bank_mask:0xf bound_ctrl:1
	v_pk_fma_f32 v[48:49], v[28:29], v[66:67], v[6:7] op_sel_hi:[1,0,1]
	v_pk_fma_f32 v[50:51], v[30:31], v[66:67], v[8:9] op_sel_hi:[1,0,1]
	v_add_f32_dpp v12, v12, v12 row_ror:4 row_mask:0xf bank_mask:0xf bound_ctrl:1
	v_add_f32_dpp v104, v100, v100 row_ror:12 row_mask:0xf bank_mask:0x5
	v_add_f32_dpp v105, v105, v105 row_ror:4 row_mask:0xf bank_mask:0xa
	v_add_f32_dpp v105, v101, v101 row_ror:12 row_mask:0xf bank_mask:0x5
	v_add_f32_dpp v12, v12, v12 row_ror:8 row_mask:0xf bank_mask:0xf bound_ctrl:1
	v_pk_fma_f32 v[6:7], v[24:25], v[12:13], v[48:49] op_sel_hi:[1,0,1] neg_lo:[1,0,0] neg_hi:[1,0,0]
	v_pk_fma_f32 v[8:9], v[26:27], v[12:13], v[50:51] op_sel_hi:[1,0,1] neg_lo:[1,0,0] neg_hi:[1,0,0]
	ds_read_b128 v[88:91], v10 offset:26880
	ds_read_b128 v[96:99], v10 offset:27392
	ds_read_b128 v[92:95], v10 offset:27136
	s_waitcnt lgkmcnt(3)
	s_nop 0
	v_fma_mix_f32 v12, v6, v36, v180 op_sel_hi:[0,1,0]
	v_fma_mix_f32 v12, v7, v36, v12 op_sel:[0,1,0] op_sel_hi:[0,1,0]
	v_fma_mix_f32 v12, v8, v37, v12 op_sel_hi:[0,1,0]
	v_fma_mix_f32 v12, v9, v37, v12 op_sel:[0,1,0] op_sel_hi:[0,1,0]
	v_fma_mix_f32 v130, v6, v22, v180 op_sel_hi:[0,1,0]
	v_fma_mix_f32 v130, v7, v22, v130 op_sel:[0,1,0] op_sel_hi:[0,1,0]
	v_add_f32_dpp v12, v12, v12 row_ror:1 row_mask:0xf bank_mask:0xf bound_ctrl:1
	v_fma_mix_f32 v130, v8, v23, v130 op_sel_hi:[0,1,0]
	v_fma_mix_f32 v130, v9, v23, v130 op_sel:[0,1,0] op_sel_hi:[0,1,0]
	v_add_f32_dpp v12, v12, v12 row_ror:2 row_mask:0xf bank_mask:0xf bound_ctrl:1
	v_pk_fma_f32 v[48:49], v[44:45], v[66:67], v[6:7] op_sel:[0,1,0]
	v_pk_fma_f32 v[50:51], v[46:47], v[66:67], v[8:9] op_sel:[0,1,0]
	v_add_f32_dpp v12, v12, v12 row_ror:4 row_mask:0xf bank_mask:0xf bound_ctrl:1
	v_add_f32_dpp v61, v61, v61 row_ror:4 row_mask:0xf bank_mask:0xa
	v_add_f32_dpp v61, v102, v102 row_ror:12 row_mask:0xf bank_mask:0x5
	v_add_f32_dpp v12, v12, v12 row_ror:8 row_mask:0xf bank_mask:0xf bound_ctrl:1
	v_pk_fma_f32 v[6:7], v[40:41], v[12:13], v[48:49] op_sel_hi:[1,0,1] neg_lo:[1,0,0] neg_hi:[1,0,0]
	v_pk_fma_f32 v[8:9], v[42:43], v[12:13], v[50:51] op_sel_hi:[1,0,1] neg_lo:[1,0,0] neg_hi:[1,0,0]
	ds_read_b128 v[110:113], v10 offset:27904
	ds_read_b128 v[106:109], v10 offset:27648
	ds_read_b128 v[118:121], v10 offset:28416
	ds_read_b128 v[114:117], v10 offset:28160
	ds_read_b128 v[70:73], v11 offset:1792
	s_waitcnt lgkmcnt(5)
	s_nop 0
	v_fma_mix_f32 v12, v6, v88, v180 op_sel_hi:[0,1,0]
	v_fma_mix_f32 v12, v7, v88, v12 op_sel:[0,1,0] op_sel_hi:[0,1,0]
	v_fma_mix_f32 v12, v8, v89, v12 op_sel_hi:[0,1,0]
	v_fma_mix_f32 v12, v9, v89, v12 op_sel:[0,1,0] op_sel_hi:[0,1,0]
	v_fma_mix_f32 v131, v6, v38, v180 op_sel_hi:[0,1,0]
	v_fma_mix_f32 v131, v7, v38, v131 op_sel:[0,1,0] op_sel_hi:[0,1,0]
	v_add_f32_dpp v12, v12, v12 row_ror:1 row_mask:0xf bank_mask:0xf bound_ctrl:1
	v_fma_mix_f32 v131, v8, v39, v131 op_sel_hi:[0,1,0]
	v_fma_mix_f32 v131, v9, v39, v131 op_sel:[0,1,0] op_sel_hi:[0,1,0]
	v_add_f32_dpp v12, v12, v12 row_ror:2 row_mask:0xf bank_mask:0xf bound_ctrl:1
	v_pk_fma_f32 v[48:49], v[96:97], v[68:69], v[6:7] op_sel_hi:[1,0,1]
	v_pk_fma_f32 v[50:51], v[98:99], v[68:69], v[8:9] op_sel_hi:[1,0,1]
	v_add_f32_dpp v12, v12, v12 row_ror:4 row_mask:0xf bank_mask:0xf bound_ctrl:1
	v_cndmask_b32_e64 v62, v105, v103, s[38:39]
	v_cndmask_b32_e64 v63, v103, v105, s[38:39]
	v_add_f32_dpp v12, v12, v12 row_ror:8 row_mask:0xf bank_mask:0xf bound_ctrl:1
	v_pk_fma_f32 v[6:7], v[92:93], v[12:13], v[48:49] op_sel_hi:[1,0,1] neg_lo:[1,0,0] neg_hi:[1,0,0]
	v_pk_fma_f32 v[8:9], v[94:95], v[12:13], v[50:51] op_sel_hi:[1,0,1] neg_lo:[1,0,0] neg_hi:[1,0,0]
	ds_read_b128 v[20:23], v10 offset:28928
	ds_read_b128 v[28:31], v10 offset:29440
	ds_read_b128 v[24:27], v10 offset:29184
	s_waitcnt lgkmcnt(4)
	s_nop 0
	v_fma_mix_f32 v12, v6, v110, v180 op_sel_hi:[0,1,0]
	v_fma_mix_f32 v12, v7, v110, v12 op_sel:[0,1,0] op_sel_hi:[0,1,0]
	v_fma_mix_f32 v12, v8, v111, v12 op_sel_hi:[0,1,0]
	v_fma_mix_f32 v12, v9, v111, v12 op_sel:[0,1,0] op_sel_hi:[0,1,0]
	v_fma_mix_f32 v132, v6, v90, v180 op_sel_hi:[0,1,0]
	v_fma_mix_f32 v132, v7, v90, v132 op_sel:[0,1,0] op_sel_hi:[0,1,0]
	v_add_f32_dpp v12, v12, v12 row_ror:1 row_mask:0xf bank_mask:0xf bound_ctrl:1
	v_fma_mix_f32 v132, v8, v91, v132 op_sel_hi:[0,1,0]
	v_fma_mix_f32 v132, v9, v91, v132 op_sel:[0,1,0] op_sel_hi:[0,1,0]
	v_add_f32_dpp v12, v12, v12 row_ror:2 row_mask:0xf bank_mask:0xf bound_ctrl:1
	v_pk_fma_f32 v[48:49], v[118:119], v[68:69], v[6:7] op_sel:[0,1,0]
	v_pk_fma_f32 v[50:51], v[120:121], v[68:69], v[8:9] op_sel:[0,1,0]
	v_add_f32_dpp v12, v12, v12 row_ror:4 row_mask:0xf bank_mask:0xf bound_ctrl:1
	v_cndmask_b32_e64 v64, v61, v104, s[38:39]
	v_cndmask_b32_e64 v65, v104, v61, s[38:39]
	v_add_f32_dpp v12, v12, v12 row_ror:8 row_mask:0xf bank_mask:0xf bound_ctrl:1
	v_pk_fma_f32 v[6:7], v[114:115], v[12:13], v[48:49] op_sel_hi:[1,0,1] neg_lo:[1,0,0] neg_hi:[1,0,0]
	v_pk_fma_f32 v[8:9], v[116:117], v[12:13], v[50:51] op_sel_hi:[1,0,1] neg_lo:[1,0,0] neg_hi:[1,0,0]
	v_pk_mul_f32 v[6:7], v[6:7], v[106:107]
	v_pk_mul_f32 v[8:9], v[8:9], v[108:109]
	ds_read_b128 v[36:39], v10 offset:29952
	ds_read_b128 v[44:47], v10 offset:30464
	ds_read_b128 v[40:43], v10 offset:30208
	s_waitcnt lgkmcnt(3)
	s_nop 0
	v_fma_mix_f32 v12, v6, v20, v180 op_sel_hi:[0,1,0]
	v_fma_mix_f32 v12, v7, v20, v12 op_sel:[0,1,0] op_sel_hi:[0,1,0]
	v_fma_mix_f32 v12, v8, v21, v12 op_sel_hi:[0,1,0]
	v_fma_mix_f32 v12, v9, v21, v12 op_sel:[0,1,0] op_sel_hi:[0,1,0]
	v_fma_mix_f32 v133, v6, v112, v180 op_sel_hi:[0,1,0]
	v_fma_mix_f32 v133, v7, v112, v133 op_sel:[0,1,0] op_sel_hi:[0,1,0]
	v_add_f32_dpp v12, v12, v12 row_ror:1 row_mask:0xf bank_mask:0xf bound_ctrl:1
	v_fma_mix_f32 v133, v8, v113, v133 op_sel_hi:[0,1,0]
	v_fma_mix_f32 v133, v9, v113, v133 op_sel:[0,1,0] op_sel_hi:[0,1,0]
	v_add_f32_dpp v12, v12, v12 row_ror:2 row_mask:0xf bank_mask:0xf bound_ctrl:1
	v_pk_fma_f32 v[48:49], v[28:29], v[70:71], v[6:7] op_sel_hi:[1,0,1]
	v_pk_fma_f32 v[50:51], v[30:31], v[70:71], v[8:9] op_sel_hi:[1,0,1]
	v_add_f32_dpp v12, v12, v12 row_ror:4 row_mask:0xf bank_mask:0xf bound_ctrl:1
	v_add_f32_dpp v62, v63, v62 quad_perm:[2,3,0,1] row_mask:0xf bank_mask:0xf bound_ctrl:1
	v_add_f32_dpp v63, v65, v64 quad_perm:[2,3,0,1] row_mask:0xf bank_mask:0xf bound_ctrl:1
	v_add_f32_dpp v12, v12, v12 row_ror:8 row_mask:0xf bank_mask:0xf bound_ctrl:1
	v_pk_fma_f32 v[6:7], v[24:25], v[12:13], v[48:49] op_sel_hi:[1,0,1] neg_lo:[1,0,0] neg_hi:[1,0,0]
	v_pk_fma_f32 v[8:9], v[26:27], v[12:13], v[50:51] op_sel_hi:[1,0,1] neg_lo:[1,0,0] neg_hi:[1,0,0]
	ds_read_b128 v[88:91], v10 offset:30976
	ds_read_b128 v[96:99], v10 offset:31488
	ds_read_b128 v[92:95], v10 offset:31232
	s_waitcnt lgkmcnt(3)
	s_nop 0
	v_fma_mix_f32 v12, v6, v36, v180 op_sel_hi:[0,1,0]
	v_fma_mix_f32 v12, v7, v36, v12 op_sel:[0,1,0] op_sel_hi:[0,1,0]
	v_fma_mix_f32 v12, v8, v37, v12 op_sel_hi:[0,1,0]
	v_fma_mix_f32 v12, v9, v37, v12 op_sel:[0,1,0] op_sel_hi:[0,1,0]
	v_fma_mix_f32 v134, v6, v22, v180 op_sel_hi:[0,1,0]
	v_fma_mix_f32 v134, v7, v22, v134 op_sel:[0,1,0] op_sel_hi:[0,1,0]
	v_add_f32_dpp v12, v12, v12 row_ror:1 row_mask:0xf bank_mask:0xf bound_ctrl:1
	v_fma_mix_f32 v134, v8, v23, v134 op_sel_hi:[0,1,0]
	v_fma_mix_f32 v134, v9, v23, v134 op_sel:[0,1,0] op_sel_hi:[0,1,0]
	v_add_f32_dpp v12, v12, v12 row_ror:2 row_mask:0xf bank_mask:0xf bound_ctrl:1
	v_pk_fma_f32 v[48:49], v[44:45], v[70:71], v[6:7] op_sel:[0,1,0]
	v_pk_fma_f32 v[50:51], v[46:47], v[70:71], v[8:9] op_sel:[0,1,0]
	v_add_f32_dpp v12, v12, v12 row_ror:4 row_mask:0xf bank_mask:0xf bound_ctrl:1
	v_cndmask_b32_e64 v65, v63, v62, s[40:41]
	v_cndmask_b32_e64 v62, v62, v63, s[40:41]
	v_add_f32_dpp v12, v12, v12 row_ror:8 row_mask:0xf bank_mask:0xf bound_ctrl:1
	v_pk_fma_f32 v[6:7], v[40:41], v[12:13], v[48:49] op_sel_hi:[1,0,1] neg_lo:[1,0,0] neg_hi:[1,0,0]
	v_pk_fma_f32 v[8:9], v[42:43], v[12:13], v[50:51] op_sel_hi:[1,0,1] neg_lo:[1,0,0] neg_hi:[1,0,0]
	ds_read_b128 v[110:113], v10 offset:32000
	ds_read_b128 v[106:109], v10 offset:31744
	ds_read_b128 v[118:121], v10 offset:32512
	ds_read_b128 v[114:117], v10 offset:32256
	ds_read_b128 v[66:69], v11 offset:2048
	s_waitcnt lgkmcnt(5)
	s_nop 0
	v_fma_mix_f32 v12, v6, v88, v180 op_sel_hi:[0,1,0]
	v_fma_mix_f32 v12, v7, v88, v12 op_sel:[0,1,0] op_sel_hi:[0,1,0]
	v_fma_mix_f32 v12, v8, v89, v12 op_sel_hi:[0,1,0]
	v_fma_mix_f32 v12, v9, v89, v12 op_sel:[0,1,0] op_sel_hi:[0,1,0]
	v_fma_mix_f32 v135, v6, v38, v180 op_sel_hi:[0,1,0]
	v_fma_mix_f32 v135, v7, v38, v135 op_sel:[0,1,0] op_sel_hi:[0,1,0]
	v_add_f32_dpp v12, v12, v12 row_ror:1 row_mask:0xf bank_mask:0xf bound_ctrl:1
	v_fma_mix_f32 v135, v8, v39, v135 op_sel_hi:[0,1,0]
	v_fma_mix_f32 v135, v9, v39, v135 op_sel:[0,1,0] op_sel_hi:[0,1,0]
	v_add_f32_dpp v12, v12, v12 row_ror:2 row_mask:0xf bank_mask:0xf bound_ctrl:1
	v_pk_fma_f32 v[48:49], v[96:97], v[72:73], v[6:7] op_sel_hi:[1,0,1]
	v_pk_fma_f32 v[50:51], v[98:99], v[72:73], v[8:9] op_sel_hi:[1,0,1]
	v_add_f32_dpp v12, v12, v12 row_ror:4 row_mask:0xf bank_mask:0xf bound_ctrl:1
	v_add_f32_dpp v62, v62, v65 quad_perm:[1,0,3,2] row_mask:0xf bank_mask:0xf bound_ctrl:1
	v_cvt_pk_bf16_f32 v62, v62, v62
	v_add_f32_dpp v12, v12, v12 row_ror:8 row_mask:0xf bank_mask:0xf bound_ctrl:1
	v_pk_fma_f32 v[6:7], v[92:93], v[12:13], v[48:49] op_sel_hi:[1,0,1] neg_lo:[1,0,0] neg_hi:[1,0,0]
	v_pk_fma_f32 v[8:9], v[94:95], v[12:13], v[50:51] op_sel_hi:[1,0,1] neg_lo:[1,0,0] neg_hi:[1,0,0]
	ds_read_b128 v[20:23], v10 offset:33024
	ds_read_b128 v[28:31], v10 offset:33536
	ds_read_b128 v[24:27], v10 offset:33280
	s_waitcnt lgkmcnt(4)
	s_nop 0
	v_fma_mix_f32 v12, v6, v110, v180 op_sel_hi:[0,1,0]
	v_fma_mix_f32 v12, v7, v110, v12 op_sel:[0,1,0] op_sel_hi:[0,1,0]
	v_fma_mix_f32 v12, v8, v111, v12 op_sel_hi:[0,1,0]
	v_fma_mix_f32 v12, v9, v111, v12 op_sel:[0,1,0] op_sel_hi:[0,1,0]
	v_fma_mix_f32 v136, v6, v90, v180 op_sel_hi:[0,1,0]
	v_fma_mix_f32 v136, v7, v90, v136 op_sel:[0,1,0] op_sel_hi:[0,1,0]
	v_add_f32_dpp v12, v12, v12 row_ror:1 row_mask:0xf bank_mask:0xf bound_ctrl:1
	v_fma_mix_f32 v136, v8, v91, v136 op_sel_hi:[0,1,0]
	v_fma_mix_f32 v136, v9, v91, v136 op_sel:[0,1,0] op_sel_hi:[0,1,0]
	v_add_f32_dpp v12, v12, v12 row_ror:2 row_mask:0xf bank_mask:0xf bound_ctrl:1
	v_pk_fma_f32 v[48:49], v[118:119], v[72:73], v[6:7] op_sel:[0,1,0]
	v_pk_fma_f32 v[50:51], v[120:121], v[72:73], v[8:9] op_sel:[0,1,0]
	v_add_f32_dpp v12, v12, v12 row_ror:4 row_mask:0xf bank_mask:0xf bound_ctrl:1
	global_store_short v[2:3], v62, off
	v_lshl_add_u64 v[2:3], v[2:3], 0, s[84:85]
	v_add_f32_dpp v12, v12, v12 row_ror:8 row_mask:0xf bank_mask:0xf bound_ctrl:1
	v_pk_fma_f32 v[6:7], v[114:115], v[12:13], v[48:49] op_sel_hi:[1,0,1] neg_lo:[1,0,0] neg_hi:[1,0,0]
	v_pk_fma_f32 v[8:9], v[116:117], v[12:13], v[50:51] op_sel_hi:[1,0,1] neg_lo:[1,0,0] neg_hi:[1,0,0]
	v_pk_mul_f32 v[6:7], v[6:7], v[106:107]
	v_pk_mul_f32 v[8:9], v[8:9], v[108:109]
	ds_read_b128 v[36:39], v10 offset:34048
	ds_read_b128 v[44:47], v10 offset:34560
	ds_read_b128 v[40:43], v10 offset:34304
	s_waitcnt lgkmcnt(3)
	s_nop 0
	v_fma_mix_f32 v12, v6, v20, v180 op_sel_hi:[0,1,0]
	v_fma_mix_f32 v12, v7, v20, v12 op_sel:[0,1,0] op_sel_hi:[0,1,0]
	v_fma_mix_f32 v12, v8, v21, v12 op_sel_hi:[0,1,0]
	v_fma_mix_f32 v12, v9, v21, v12 op_sel:[0,1,0] op_sel_hi:[0,1,0]
	v_fma_mix_f32 v137, v6, v112, v180 op_sel_hi:[0,1,0]
	v_fma_mix_f32 v137, v7, v112, v137 op_sel:[0,1,0] op_sel_hi:[0,1,0]
	v_add_f32_dpp v12, v12, v12 row_ror:1 row_mask:0xf bank_mask:0xf bound_ctrl:1
	v_fma_mix_f32 v137, v8, v113, v137 op_sel_hi:[0,1,0]
	v_fma_mix_f32 v137, v9, v113, v137 op_sel:[0,1,0] op_sel_hi:[0,1,0]
	v_add_f32_dpp v12, v12, v12 row_ror:2 row_mask:0xf bank_mask:0xf bound_ctrl:1
	v_pk_fma_f32 v[48:49], v[28:29], v[66:67], v[6:7] op_sel_hi:[1,0,1]
	v_pk_fma_f32 v[50:51], v[30:31], v[66:67], v[8:9] op_sel_hi:[1,0,1]
	v_add_f32_dpp v12, v12, v12 row_ror:4 row_mask:0xf bank_mask:0xf bound_ctrl:1
	s_nop 1
	s_nop 0
	v_add_f32_dpp v12, v12, v12 row_ror:8 row_mask:0xf bank_mask:0xf bound_ctrl:1
	v_pk_fma_f32 v[6:7], v[24:25], v[12:13], v[48:49] op_sel_hi:[1,0,1] neg_lo:[1,0,0] neg_hi:[1,0,0]
	v_pk_fma_f32 v[8:9], v[26:27], v[12:13], v[50:51] op_sel_hi:[1,0,1] neg_lo:[1,0,0] neg_hi:[1,0,0]
	ds_read_b128 v[88:91], v10 offset:35072
	ds_read_b128 v[96:99], v10 offset:35584
	ds_read_b128 v[92:95], v10 offset:35328
	s_waitcnt lgkmcnt(3)
	s_nop 0
	v_fma_mix_f32 v12, v6, v36, v180 op_sel_hi:[0,1,0]
	v_fma_mix_f32 v12, v7, v36, v12 op_sel:[0,1,0] op_sel_hi:[0,1,0]
	v_fma_mix_f32 v12, v8, v37, v12 op_sel_hi:[0,1,0]
	v_fma_mix_f32 v12, v9, v37, v12 op_sel:[0,1,0] op_sel_hi:[0,1,0]
	v_fma_mix_f32 v52, v6, v22, v180 op_sel_hi:[0,1,0]
	v_fma_mix_f32 v52, v7, v22, v52 op_sel:[0,1,0] op_sel_hi:[0,1,0]
	v_add_f32_dpp v12, v12, v12 row_ror:1 row_mask:0xf bank_mask:0xf bound_ctrl:1
	v_fma_mix_f32 v52, v8, v23, v52 op_sel_hi:[0,1,0]
	v_fma_mix_f32 v52, v9, v23, v52 op_sel:[0,1,0] op_sel_hi:[0,1,0]
	v_add_f32_dpp v12, v12, v12 row_ror:2 row_mask:0xf bank_mask:0xf bound_ctrl:1
	v_pk_fma_f32 v[48:49], v[44:45], v[66:67], v[6:7] op_sel:[0,1,0]
	v_pk_fma_f32 v[50:51], v[46:47], v[66:67], v[8:9] op_sel:[0,1,0]
	v_add_f32_dpp v12, v12, v12 row_ror:4 row_mask:0xf bank_mask:0xf bound_ctrl:1
	v_add_f32_dpp v130, v130, v130 row_ror:8 row_mask:0xf bank_mask:0xc
	v_add_f32_dpp v130, v122, v122 row_ror:8 row_mask:0xf bank_mask:0x3
	v_add_f32_dpp v131, v131, v131 row_ror:8 row_mask:0xf bank_mask:0xc
	v_add_f32_dpp v12, v12, v12 row_ror:8 row_mask:0xf bank_mask:0xf bound_ctrl:1
	v_pk_fma_f32 v[6:7], v[40:41], v[12:13], v[48:49] op_sel_hi:[1,0,1] neg_lo:[1,0,0] neg_hi:[1,0,0]
	v_pk_fma_f32 v[8:9], v[42:43], v[12:13], v[50:51] op_sel_hi:[1,0,1] neg_lo:[1,0,0] neg_hi:[1,0,0]
	ds_read_b128 v[110:113], v10 offset:36096
	ds_read_b128 v[106:109], v10 offset:35840
	ds_read_b128 v[118:121], v10 offset:36608
	ds_read_b128 v[114:117], v10 offset:36352
	ds_read_b128 v[70:73], v11 offset:2304
	s_waitcnt lgkmcnt(5)
	s_nop 0
	v_fma_mix_f32 v12, v6, v88, v180 op_sel_hi:[0,1,0]
	v_fma_mix_f32 v12, v7, v88, v12 op_sel:[0,1,0] op_sel_hi:[0,1,0]
	v_fma_mix_f32 v12, v8, v89, v12 op_sel_hi:[0,1,0]
	v_fma_mix_f32 v12, v9, v89, v12 op_sel:[0,1,0] op_sel_hi:[0,1,0]
	v_fma_mix_f32 v53, v6, v38, v180 op_sel_hi:[0,1,0]
	v_fma_mix_f32 v53, v7, v38, v53 op_sel:[0,1,0] op_sel_hi:[0,1,0]
	v_add_f32_dpp v12, v12, v12 row_ror:1 row_mask:0xf bank_mask:0xf bound_ctrl:1
	v_fma_mix_f32 v53, v8, v39, v53 op_sel_hi:[0,1,0]
	v_fma_mix_f32 v53, v9, v39, v53 op_sel:[0,1,0] op_sel_hi:[0,1,0]
	v_add_f32_dpp v12, v12, v12 row_ror:2 row_mask:0xf bank_mask:0xf bound_ctrl:1
	v_pk_fma_f32 v[48:49], v[96:97], v[68:69], v[6:7] op_sel_hi:[1,0,1]
	v_pk_fma_f32 v[50:51], v[98:99], v[68:69], v[8:9] op_sel_hi:[1,0,1]
	v_add_f32_dpp v12, v12, v12 row_ror:4 row_mask:0xf bank_mask:0xf bound_ctrl:1
	v_add_f32_dpp v131, v123, v123 row_ror:8 row_mask:0xf bank_mask:0x3
	v_add_f32_dpp v132, v132, v132 row_ror:8 row_mask:0xf bank_mask:0xc
	v_add_f32_dpp v132, v124, v124 row_ror:8 row_mask:0xf bank_mask:0x3
	v_add_f32_dpp v12, v12, v12 row_ror:8 row_mask:0xf bank_mask:0xf bound_ctrl:1
	v_pk_fma_f32 v[6:7], v[92:93], v[12:13], v[48:49] op_sel_hi:[1,0,1] neg_lo:[1,0,0] neg_hi:[1,0,0]
	v_pk_fma_f32 v[8:9], v[94:95], v[12:13], v[50:51] op_sel_hi:[1,0,1] neg_lo:[1,0,0] neg_hi:[1,0,0]
	ds_read_b128 v[20:23], v10 offset:37120
	ds_read_b128 v[28:31], v10 offset:37632
	ds_read_b128 v[24:27], v10 offset:37376
	s_waitcnt lgkmcnt(4)
	s_nop 0
	v_fma_mix_f32 v12, v6, v110, v180 op_sel_hi:[0,1,0]
	v_fma_mix_f32 v12, v7, v110, v12 op_sel:[0,1,0] op_sel_hi:[0,1,0]
	v_fma_mix_f32 v12, v8, v111, v12 op_sel_hi:[0,1,0]
	v_fma_mix_f32 v12, v9, v111, v12 op_sel:[0,1,0] op_sel_hi:[0,1,0]
	v_fma_mix_f32 v54, v6, v90, v180 op_sel_hi:[0,1,0]
	v_fma_mix_f32 v54, v7, v90, v54 op_sel:[0,1,0] op_sel_hi:[0,1,0]
	v_add_f32_dpp v12, v12, v12 row_ror:1 row_mask:0xf bank_mask:0xf bound_ctrl:1
	v_fma_mix_f32 v54, v8, v91, v54 op_sel_hi:[0,1,0]
	v_fma_mix_f32 v54, v9, v91, v54 op_sel:[0,1,0] op_sel_hi:[0,1,0]
	v_add_f32_dpp v12, v12, v12 row_ror:2 row_mask:0xf bank_mask:0xf bound_ctrl:1
	v_pk_fma_f32 v[48:49], v[118:119], v[68:69], v[6:7] op_sel:[0,1,0]
	v_pk_fma_f32 v[50:51], v[120:121], v[68:69], v[8:9] op_sel:[0,1,0]
	v_add_f32_dpp v12, v12, v12 row_ror:4 row_mask:0xf bank_mask:0xf bound_ctrl:1
	v_add_f32_dpp v133, v133, v133 row_ror:8 row_mask:0xf bank_mask:0xc
	v_add_f32_dpp v133, v125, v125 row_ror:8 row_mask:0xf bank_mask:0x3
	v_add_f32_dpp v134, v134, v134 row_ror:8 row_mask:0xf bank_mask:0xc
	v_add_f32_dpp v12, v12, v12 row_ror:8 row_mask:0xf bank_mask:0xf bound_ctrl:1
	v_pk_fma_f32 v[6:7], v[114:115], v[12:13], v[48:49] op_sel_hi:[1,0,1] neg_lo:[1,0,0] neg_hi:[1,0,0]
	v_pk_fma_f32 v[8:9], v[116:117], v[12:13], v[50:51] op_sel_hi:[1,0,1] neg_lo:[1,0,0] neg_hi:[1,0,0]
	v_pk_mul_f32 v[6:7], v[6:7], v[106:107]
	v_pk_mul_f32 v[8:9], v[8:9], v[108:109]
	ds_read_b128 v[36:39], v10 offset:38144
	ds_read_b128 v[44:47], v10 offset:38656
	ds_read_b128 v[40:43], v10 offset:38400
	s_waitcnt lgkmcnt(3)
	s_nop 0
	v_fma_mix_f32 v12, v6, v20, v180 op_sel_hi:[0,1,0]
	v_fma_mix_f32 v12, v7, v20, v12 op_sel:[0,1,0] op_sel_hi:[0,1,0]
	v_fma_mix_f32 v12, v8, v21, v12 op_sel_hi:[0,1,0]
	v_fma_mix_f32 v12, v9, v21, v12 op_sel:[0,1,0] op_sel_hi:[0,1,0]
	v_fma_mix_f32 v55, v6, v112, v180 op_sel_hi:[0,1,0]
	v_fma_mix_f32 v55, v7, v112, v55 op_sel:[0,1,0] op_sel_hi:[0,1,0]
	v_add_f32_dpp v12, v12, v12 row_ror:1 row_mask:0xf bank_mask:0xf bound_ctrl:1
	v_fma_mix_f32 v55, v8, v113, v55 op_sel_hi:[0,1,0]
	v_fma_mix_f32 v55, v9, v113, v55 op_sel:[0,1,0] op_sel_hi:[0,1,0]
	v_add_f32_dpp v12, v12, v12 row_ror:2 row_mask:0xf bank_mask:0xf bound_ctrl:1
	v_pk_fma_f32 v[48:49], v[28:29], v[70:71], v[6:7] op_sel_hi:[1,0,1]
	v_pk_fma_f32 v[50:51], v[30:31], v[70:71], v[8:9] op_sel_hi:[1,0,1]
	v_add_f32_dpp v12, v12, v12 row_ror:4 row_mask:0xf bank_mask:0xf bound_ctrl:1
	v_add_f32_dpp v134, v126, v126 row_ror:8 row_mask:0xf bank_mask:0x3
	v_add_f32_dpp v135, v135, v135 row_ror:8 row_mask:0xf bank_mask:0xc
	v_add_f32_dpp v135, v127, v127 row_ror:8 row_mask:0xf bank_mask:0x3
	v_add_f32_dpp v12, v12, v12 row_ror:8 row_mask:0xf bank_mask:0xf bound_ctrl:1
	v_pk_fma_f32 v[6:7], v[24:25], v[12:13], v[48:49] op_sel_hi:[1,0,1] neg_lo:[1,0,0] neg_hi:[1,0,0]
	v_pk_fma_f32 v[8:9], v[26:27], v[12:13], v[50:51] op_sel_hi:[1,0,1] neg_lo:[1,0,0] neg_hi:[1,0,0]
	ds_read_b128 v[88:91], v10 offset:39168
	ds_read_b128 v[96:99], v10 offset:39680
	ds_read_b128 v[92:95], v10 offset:39424
	s_waitcnt lgkmcnt(3)
	s_nop 0
	v_fma_mix_f32 v12, v6, v36, v180 op_sel_hi:[0,1,0]
	v_fma_mix_f32 v12, v7, v36, v12 op_sel:[0,1,0] op_sel_hi:[0,1,0]
	v_fma_mix_f32 v12, v8, v37, v12 op_sel_hi:[0,1,0]
	v_fma_mix_f32 v12, v9, v37, v12 op_sel:[0,1,0] op_sel_hi:[0,1,0]
	v_fma_mix_f32 v56, v6, v22, v180 op_sel_hi:[0,1,0]
	v_fma_mix_f32 v56, v7, v22, v56 op_sel:[0,1,0] op_sel_hi:[0,1,0]
	v_add_f32_dpp v12, v12, v12 row_ror:1 row_mask:0xf bank_mask:0xf bound_ctrl:1
	v_fma_mix_f32 v56, v8, v23, v56 op_sel_hi:[0,1,0]
	v_fma_mix_f32 v56, v9, v23, v56 op_sel:[0,1,0] op_sel_hi:[0,1,0]
	v_add_f32_dpp v12, v12, v12 row_ror:2 row_mask:0xf bank_mask:0xf bound_ctrl:1
	v_pk_fma_f32 v[48:49], v[44:45], v[70:71], v[6:7] op_sel:[0,1,0]
	v_pk_fma_f32 v[50:51], v[46:47], v[70:71], v[8:9] op_sel:[0,1,0]
	v_add_f32_dpp v12, v12, v12 row_ror:4 row_mask:0xf bank_mask:0xf bound_ctrl:1
	v_add_f32_dpp v136, v136, v136 row_ror:8 row_mask:0xf bank_mask:0xc
	v_add_f32_dpp v136, v128, v128 row_ror:8 row_mask:0xf bank_mask:0x3
	v_add_f32_dpp v12, v12, v12 row_ror:8 row_mask:0xf bank_mask:0xf bound_ctrl:1
	v_pk_fma_f32 v[6:7], v[40:41], v[12:13], v[48:49] op_sel_hi:[1,0,1] neg_lo:[1,0,0] neg_hi:[1,0,0]
	v_pk_fma_f32 v[8:9], v[42:43], v[12:13], v[50:51] op_sel_hi:[1,0,1] neg_lo:[1,0,0] neg_hi:[1,0,0]
	ds_read_b128 v[110:113], v10 offset:40192
	ds_read_b128 v[106:109], v10 offset:39936
	ds_read_b128 v[118:121], v10 offset:40704
	ds_read_b128 v[114:117], v10 offset:40448
	ds_read_b128 v[66:69], v11 offset:2560
	s_waitcnt lgkmcnt(5)
	s_nop 0
	v_fma_mix_f32 v12, v6, v88, v180 op_sel_hi:[0,1,0]
	v_fma_mix_f32 v12, v7, v88, v12 op_sel:[0,1,0] op_sel_hi:[0,1,0]
	v_fma_mix_f32 v12, v8, v89, v12 op_sel_hi:[0,1,0]
	v_fma_mix_f32 v12, v9, v89, v12 op_sel:[0,1,0] op_sel_hi:[0,1,0]
	v_fma_mix_f32 v57, v6, v38, v180 op_sel_hi:[0,1,0]
	v_fma_mix_f32 v57, v7, v38, v57 op_sel:[0,1,0] op_sel_hi:[0,1,0]
	v_add_f32_dpp v12, v12, v12 row_ror:1 row_mask:0xf bank_mask:0xf bound_ctrl:1
	v_fma_mix_f32 v57, v8, v39, v57 op_sel_hi:[0,1,0]
	v_fma_mix_f32 v57, v9, v39, v57 op_sel:[0,1,0] op_sel_hi:[0,1,0]
	v_add_f32_dpp v12, v12, v12 row_ror:2 row_mask:0xf bank_mask:0xf bound_ctrl:1
	v_pk_fma_f32 v[48:49], v[96:97], v[72:73], v[6:7] op_sel_hi:[1,0,1]
	v_pk_fma_f32 v[50:51], v[98:99], v[72:73], v[8:9] op_sel_hi:[1,0,1]
	v_add_f32_dpp v12, v12, v12 row_ror:4 row_mask:0xf bank_mask:0xf bound_ctrl:1
	v_add_f32_dpp v137, v137, v137 row_ror:8 row_mask:0xf bank_mask:0xc
	v_add_f32_dpp v137, v129, v129 row_ror:8 row_mask:0xf bank_mask:0x3
	v_add_f32_dpp v12, v12, v12 row_ror:8 row_mask:0xf bank_mask:0xf bound_ctrl:1
	v_pk_fma_f32 v[6:7], v[92:93], v[12:13], v[48:49] op_sel_hi:[1,0,1] neg_lo:[1,0,0] neg_hi:[1,0,0]
	v_pk_fma_f32 v[8:9], v[94:95], v[12:13], v[50:51] op_sel_hi:[1,0,1] neg_lo:[1,0,0] neg_hi:[1,0,0]
	ds_read_b128 v[20:23], v10 offset:41216
	ds_read_b128 v[28:31], v10 offset:41728
	ds_read_b128 v[24:27], v10 offset:41472
	s_waitcnt lgkmcnt(4)
	s_nop 0
	v_fma_mix_f32 v12, v6, v110, v180 op_sel_hi:[0,1,0]
	v_fma_mix_f32 v12, v7, v110, v12 op_sel:[0,1,0] op_sel_hi:[0,1,0]
	v_fma_mix_f32 v12, v8, v111, v12 op_sel_hi:[0,1,0]
	v_fma_mix_f32 v12, v9, v111, v12 op_sel:[0,1,0] op_sel_hi:[0,1,0]
	v_fma_mix_f32 v81, v6, v90, v180 op_sel_hi:[0,1,0]
	v_fma_mix_f32 v81, v7, v90, v81 op_sel:[0,1,0] op_sel_hi:[0,1,0]
	v_add_f32_dpp v12, v12, v12 row_ror:1 row_mask:0xf bank_mask:0xf bound_ctrl:1
	v_fma_mix_f32 v81, v8, v91, v81 op_sel_hi:[0,1,0]
	v_fma_mix_f32 v81, v9, v91, v81 op_sel:[0,1,0] op_sel_hi:[0,1,0]
	v_add_f32_dpp v12, v12, v12 row_ror:2 row_mask:0xf bank_mask:0xf bound_ctrl:1
	v_pk_fma_f32 v[48:49], v[118:119], v[72:73], v[6:7] op_sel:[0,1,0]
	v_pk_fma_f32 v[50:51], v[120:121], v[72:73], v[8:9] op_sel:[0,1,0]
	v_add_f32_dpp v12, v12, v12 row_ror:4 row_mask:0xf bank_mask:0xf bound_ctrl:1
	v_add_f32_dpp v134, v134, v134 row_ror:4 row_mask:0xf bank_mask:0xa
	v_add_f32_dpp v134, v130, v130 row_ror:12 row_mask:0xf bank_mask:0x5
	v_add_f32_dpp v135, v135, v135 row_ror:4 row_mask:0xf bank_mask:0xa
	v_add_f32_dpp v12, v12, v12 row_ror:8 row_mask:0xf bank_mask:0xf bound_ctrl:1
	v_pk_fma_f32 v[6:7], v[114:115], v[12:13], v[48:49] op_sel_hi:[1,0,1] neg_lo:[1,0,0] neg_hi:[1,0,0]
	v_pk_fma_f32 v[8:9], v[116:117], v[12:13], v[50:51] op_sel_hi:[1,0,1] neg_lo:[1,0,0] neg_hi:[1,0,0]
	v_pk_mul_f32 v[6:7], v[6:7], v[106:107]
	v_pk_mul_f32 v[8:9], v[8:9], v[108:109]
	ds_read_b128 v[36:39], v10 offset:42240
	ds_read_b128 v[44:47], v10 offset:42752
	ds_read_b128 v[40:43], v10 offset:42496
	s_waitcnt lgkmcnt(3)
	s_nop 0
	v_fma_mix_f32 v12, v6, v20, v180 op_sel_hi:[0,1,0]
	v_fma_mix_f32 v12, v7, v20, v12 op_sel:[0,1,0] op_sel_hi:[0,1,0]
	v_fma_mix_f32 v12, v8, v21, v12 op_sel_hi:[0,1,0]
	v_fma_mix_f32 v12, v9, v21, v12 op_sel:[0,1,0] op_sel_hi:[0,1,0]
	v_fma_mix_f32 v82, v6, v112, v180 op_sel_hi:[0,1,0]
	v_fma_mix_f32 v82, v7, v112, v82 op_sel:[0,1,0] op_sel_hi:[0,1,0]
	v_add_f32_dpp v12, v12, v12 row_ror:1 row_mask:0xf bank_mask:0xf bound_ctrl:1
	v_fma_mix_f32 v82, v8, v113, v82 op_sel_hi:[0,1,0]
	v_fma_mix_f32 v82, v9, v113, v82 op_sel:[0,1,0] op_sel_hi:[0,1,0]
	v_add_f32_dpp v12, v12, v12 row_ror:2 row_mask:0xf bank_mask:0xf bound_ctrl:1
	v_pk_fma_f32 v[48:49], v[28:29], v[66:67], v[6:7] op_sel_hi:[1,0,1]
	v_pk_fma_f32 v[50:51], v[30:31], v[66:67], v[8:9] op_sel_hi:[1,0,1]
	v_add_f32_dpp v12, v12, v12 row_ror:4 row_mask:0xf bank_mask:0xf bound_ctrl:1
	v_add_f32_dpp v135, v131, v131 row_ror:12 row_mask:0xf bank_mask:0x5
	v_add_f32_dpp v136, v136, v136 row_ror:4 row_mask:0xf bank_mask:0xa
	v_add_f32_dpp v136, v132, v132 row_ror:12 row_mask:0xf bank_mask:0x5
	v_add_f32_dpp v12, v12, v12 row_ror:8 row_mask:0xf bank_mask:0xf bound_ctrl:1
	v_pk_fma_f32 v[6:7], v[24:25], v[12:13], v[48:49] op_sel_hi:[1,0,1] neg_lo:[1,0,0] neg_hi:[1,0,0]
	v_pk_fma_f32 v[8:9], v[26:27], v[12:13], v[50:51] op_sel_hi:[1,0,1] neg_lo:[1,0,0] neg_hi:[1,0,0]
	ds_read_b128 v[88:91], v10 offset:43264
	ds_read_b128 v[96:99], v10 offset:43776
	ds_read_b128 v[92:95], v10 offset:43520
	s_waitcnt lgkmcnt(3)
	s_nop 0
	v_fma_mix_f32 v12, v6, v36, v180 op_sel_hi:[0,1,0]
	v_fma_mix_f32 v12, v7, v36, v12 op_sel:[0,1,0] op_sel_hi:[0,1,0]
	v_fma_mix_f32 v12, v8, v37, v12 op_sel_hi:[0,1,0]
	v_fma_mix_f32 v12, v9, v37, v12 op_sel:[0,1,0] op_sel_hi:[0,1,0]
	v_fma_mix_f32 v83, v6, v22, v180 op_sel_hi:[0,1,0]
	v_fma_mix_f32 v83, v7, v22, v83 op_sel:[0,1,0] op_sel_hi:[0,1,0]
	v_add_f32_dpp v12, v12, v12 row_ror:1 row_mask:0xf bank_mask:0xf bound_ctrl:1
	v_fma_mix_f32 v83, v8, v23, v83 op_sel_hi:[0,1,0]
	v_fma_mix_f32 v83, v9, v23, v83 op_sel:[0,1,0] op_sel_hi:[0,1,0]
	v_add_f32_dpp v12, v12, v12 row_ror:2 row_mask:0xf bank_mask:0xf bound_ctrl:1
	v_pk_fma_f32 v[48:49], v[44:45], v[66:67], v[6:7] op_sel:[0,1,0]
	v_pk_fma_f32 v[50:51], v[46:47], v[66:67], v[8:9] op_sel:[0,1,0]
	v_add_f32_dpp v12, v12, v12 row_ror:4 row_mask:0xf bank_mask:0xf bound_ctrl:1
	v_add_f32_dpp v137, v137, v137 row_ror:4 row_mask:0xf bank_mask:0xa
	v_add_f32_dpp v137, v133, v133 row_ror:12 row_mask:0xf bank_mask:0x5
	v_add_f32_dpp v12, v12, v12 row_ror:8 row_mask:0xf bank_mask:0xf bound_ctrl:1
	v_pk_fma_f32 v[6:7], v[40:41], v[12:13], v[48:49] op_sel_hi:[1,0,1] neg_lo:[1,0,0] neg_hi:[1,0,0]
	v_pk_fma_f32 v[8:9], v[42:43], v[12:13], v[50:51] op_sel_hi:[1,0,1] neg_lo:[1,0,0] neg_hi:[1,0,0]
	ds_read_b128 v[110:113], v10 offset:44288
	ds_read_b128 v[106:109], v10 offset:44032
	ds_read_b128 v[118:121], v10 offset:44800
	ds_read_b128 v[114:117], v10 offset:44544
	ds_read_b128 v[70:73], v11 offset:2816
	s_waitcnt lgkmcnt(5)
	s_nop 0
	v_fma_mix_f32 v12, v6, v88, v180 op_sel_hi:[0,1,0]
	v_fma_mix_f32 v12, v7, v88, v12 op_sel:[0,1,0] op_sel_hi:[0,1,0]
	v_fma_mix_f32 v12, v8, v89, v12 op_sel_hi:[0,1,0]
	v_fma_mix_f32 v12, v9, v89, v12 op_sel:[0,1,0] op_sel_hi:[0,1,0]
	v_fma_mix_f32 v100, v6, v38, v180 op_sel_hi:[0,1,0]
	v_fma_mix_f32 v100, v7, v38, v100 op_sel:[0,1,0] op_sel_hi:[0,1,0]
	v_add_f32_dpp v12, v12, v12 row_ror:1 row_mask:0xf bank_mask:0xf bound_ctrl:1
	v_fma_mix_f32 v100, v8, v39, v100 op_sel_hi:[0,1,0]
	v_fma_mix_f32 v100, v9, v39, v100 op_sel:[0,1,0] op_sel_hi:[0,1,0]
	v_add_f32_dpp v12, v12, v12 row_ror:2 row_mask:0xf bank_mask:0xf bound_ctrl:1
	v_pk_fma_f32 v[48:49], v[96:97], v[68:69], v[6:7] op_sel_hi:[1,0,1]
	v_pk_fma_f32 v[50:51], v[98:99], v[68:69], v[8:9] op_sel_hi:[1,0,1]
	v_add_f32_dpp v12, v12, v12 row_ror:4 row_mask:0xf bank_mask:0xf bound_ctrl:1
	v_cndmask_b32_e64 v62, v136, v134, s[38:39]
	v_cndmask_b32_e64 v63, v134, v136, s[38:39]
	v_add_f32_dpp v12, v12, v12 row_ror:8 row_mask:0xf bank_mask:0xf bound_ctrl:1
	v_pk_fma_f32 v[6:7], v[92:93], v[12:13], v[48:49] op_sel_hi:[1,0,1] neg_lo:[1,0,0] neg_hi:[1,0,0]
	v_pk_fma_f32 v[8:9], v[94:95], v[12:13], v[50:51] op_sel_hi:[1,0,1] neg_lo:[1,0,0] neg_hi:[1,0,0]
	ds_read_b128 v[20:23], v10 offset:45312
	ds_read_b128 v[28:31], v10 offset:45824
	ds_read_b128 v[24:27], v10 offset:45568
	s_waitcnt lgkmcnt(4)
	s_nop 0
	v_fma_mix_f32 v12, v6, v110, v180 op_sel_hi:[0,1,0]
	v_fma_mix_f32 v12, v7, v110, v12 op_sel:[0,1,0] op_sel_hi:[0,1,0]
	v_fma_mix_f32 v12, v8, v111, v12 op_sel_hi:[0,1,0]
	v_fma_mix_f32 v12, v9, v111, v12 op_sel:[0,1,0] op_sel_hi:[0,1,0]
	v_fma_mix_f32 v101, v6, v90, v180 op_sel_hi:[0,1,0]
	v_fma_mix_f32 v101, v7, v90, v101 op_sel:[0,1,0] op_sel_hi:[0,1,0]
	v_add_f32_dpp v12, v12, v12 row_ror:1 row_mask:0xf bank_mask:0xf bound_ctrl:1
	v_fma_mix_f32 v101, v8, v91, v101 op_sel_hi:[0,1,0]
	v_fma_mix_f32 v101, v9, v91, v101 op_sel:[0,1,0] op_sel_hi:[0,1,0]
	v_add_f32_dpp v12, v12, v12 row_ror:2 row_mask:0xf bank_mask:0xf bound_ctrl:1
	v_pk_fma_f32 v[48:49], v[118:119], v[68:69], v[6:7] op_sel:[0,1,0]
	v_pk_fma_f32 v[50:51], v[120:121], v[68:69], v[8:9] op_sel:[0,1,0]
	v_add_f32_dpp v12, v12, v12 row_ror:4 row_mask:0xf bank_mask:0xf bound_ctrl:1
	v_cndmask_b32_e64 v64, v137, v135, s[38:39]
	v_cndmask_b32_e64 v65, v135, v137, s[38:39]
	v_add_f32_dpp v12, v12, v12 row_ror:8 row_mask:0xf bank_mask:0xf bound_ctrl:1
	v_pk_fma_f32 v[6:7], v[114:115], v[12:13], v[48:49] op_sel_hi:[1,0,1] neg_lo:[1,0,0] neg_hi:[1,0,0]
	v_pk_fma_f32 v[8:9], v[116:117], v[12:13], v[50:51] op_sel_hi:[1,0,1] neg_lo:[1,0,0] neg_hi:[1,0,0]
	v_pk_mul_f32 v[6:7], v[6:7], v[106:107]
	v_pk_mul_f32 v[8:9], v[8:9], v[108:109]
	ds_read_b128 v[36:39], v10 offset:46336
	ds_read_b128 v[44:47], v10 offset:46848
	ds_read_b128 v[40:43], v10 offset:46592
	s_waitcnt lgkmcnt(3)
	s_nop 0
	v_fma_mix_f32 v12, v6, v20, v180 op_sel_hi:[0,1,0]
	v_fma_mix_f32 v12, v7, v20, v12 op_sel:[0,1,0] op_sel_hi:[0,1,0]
	v_fma_mix_f32 v12, v8, v21, v12 op_sel_hi:[0,1,0]
	v_fma_mix_f32 v12, v9, v21, v12 op_sel:[0,1,0] op_sel_hi:[0,1,0]
	v_fma_mix_f32 v102, v6, v112, v180 op_sel_hi:[0,1,0]
	v_fma_mix_f32 v102, v7, v112, v102 op_sel:[0,1,0] op_sel_hi:[0,1,0]
	v_add_f32_dpp v12, v12, v12 row_ror:1 row_mask:0xf bank_mask:0xf bound_ctrl:1
	v_fma_mix_f32 v102, v8, v113, v102 op_sel_hi:[0,1,0]
	v_fma_mix_f32 v102, v9, v113, v102 op_sel:[0,1,0] op_sel_hi:[0,1,0]
	v_add_f32_dpp v12, v12, v12 row_ror:2 row_mask:0xf bank_mask:0xf bound_ctrl:1
	v_pk_fma_f32 v[48:49], v[28:29], v[70:71], v[6:7] op_sel_hi:[1,0,1]
	v_pk_fma_f32 v[50:51], v[30:31], v[70:71], v[8:9] op_sel_hi:[1,0,1]
	v_add_f32_dpp v12, v12, v12 row_ror:4 row_mask:0xf bank_mask:0xf bound_ctrl:1
	v_add_f32_dpp v62, v63, v62 quad_perm:[2,3,0,1] row_mask:0xf bank_mask:0xf bound_ctrl:1
	v_add_f32_dpp v63, v65, v64 quad_perm:[2,3,0,1] row_mask:0xf bank_mask:0xf bound_ctrl:1
	v_add_f32_dpp v12, v12, v12 row_ror:8 row_mask:0xf bank_mask:0xf bound_ctrl:1
	v_pk_fma_f32 v[6:7], v[24:25], v[12:13], v[48:49] op_sel_hi:[1,0,1] neg_lo:[1,0,0] neg_hi:[1,0,0]
	v_pk_fma_f32 v[8:9], v[26:27], v[12:13], v[50:51] op_sel_hi:[1,0,1] neg_lo:[1,0,0] neg_hi:[1,0,0]
	ds_read_b128 v[88:91], v10 offset:47360
	ds_read_b128 v[96:99], v10 offset:47872
	ds_read_b128 v[92:95], v10 offset:47616
	s_waitcnt lgkmcnt(3)
	s_nop 0
	v_fma_mix_f32 v12, v6, v36, v180 op_sel_hi:[0,1,0]
	v_fma_mix_f32 v12, v7, v36, v12 op_sel:[0,1,0] op_sel_hi:[0,1,0]
	v_fma_mix_f32 v12, v8, v37, v12 op_sel_hi:[0,1,0]
	v_fma_mix_f32 v12, v9, v37, v12 op_sel:[0,1,0] op_sel_hi:[0,1,0]
	v_fma_mix_f32 v103, v6, v22, v180 op_sel_hi:[0,1,0]
	v_fma_mix_f32 v103, v7, v22, v103 op_sel:[0,1,0] op_sel_hi:[0,1,0]
	v_add_f32_dpp v12, v12, v12 row_ror:1 row_mask:0xf bank_mask:0xf bound_ctrl:1
	v_fma_mix_f32 v103, v8, v23, v103 op_sel_hi:[0,1,0]
	v_fma_mix_f32 v103, v9, v23, v103 op_sel:[0,1,0] op_sel_hi:[0,1,0]
	v_add_f32_dpp v12, v12, v12 row_ror:2 row_mask:0xf bank_mask:0xf bound_ctrl:1
	v_pk_fma_f32 v[48:49], v[44:45], v[70:71], v[6:7] op_sel:[0,1,0]
	v_pk_fma_f32 v[50:51], v[46:47], v[70:71], v[8:9] op_sel:[0,1,0]
	v_add_f32_dpp v12, v12, v12 row_ror:4 row_mask:0xf bank_mask:0xf bound_ctrl:1
	v_cndmask_b32_e64 v65, v63, v62, s[40:41]
	v_cndmask_b32_e64 v62, v62, v63, s[40:41]
	v_add_f32_dpp v12, v12, v12 row_ror:8 row_mask:0xf bank_mask:0xf bound_ctrl:1
	v_pk_fma_f32 v[6:7], v[40:41], v[12:13], v[48:49] op_sel_hi:[1,0,1] neg_lo:[1,0,0] neg_hi:[1,0,0]
	v_pk_fma_f32 v[8:9], v[42:43], v[12:13], v[50:51] op_sel_hi:[1,0,1] neg_lo:[1,0,0] neg_hi:[1,0,0]
	ds_read_b128 v[110:113], v10 offset:48384
	ds_read_b128 v[106:109], v10 offset:48128
	ds_read_b128 v[118:121], v10 offset:48896
	ds_read_b128 v[114:117], v10 offset:48640
	ds_read_b128 v[66:69], v11 offset:3072
	s_waitcnt lgkmcnt(5)
	s_nop 0
	v_fma_mix_f32 v12, v6, v88, v180 op_sel_hi:[0,1,0]
	v_fma_mix_f32 v12, v7, v88, v12 op_sel:[0,1,0] op_sel_hi:[0,1,0]
	v_fma_mix_f32 v12, v8, v89, v12 op_sel_hi:[0,1,0]
	v_fma_mix_f32 v12, v9, v89, v12 op_sel:[0,1,0] op_sel_hi:[0,1,0]
	v_fma_mix_f32 v104, v6, v38, v180 op_sel_hi:[0,1,0]
	v_fma_mix_f32 v104, v7, v38, v104 op_sel:[0,1,0] op_sel_hi:[0,1,0]
	v_add_f32_dpp v12, v12, v12 row_ror:1 row_mask:0xf bank_mask:0xf bound_ctrl:1
	v_fma_mix_f32 v104, v8, v39, v104 op_sel_hi:[0,1,0]
	v_fma_mix_f32 v104, v9, v39, v104 op_sel:[0,1,0] op_sel_hi:[0,1,0]
	v_add_f32_dpp v12, v12, v12 row_ror:2 row_mask:0xf bank_mask:0xf bound_ctrl:1
	v_pk_fma_f32 v[48:49], v[96:97], v[72:73], v[6:7] op_sel_hi:[1,0,1]
	v_pk_fma_f32 v[50:51], v[98:99], v[72:73], v[8:9] op_sel_hi:[1,0,1]
	v_add_f32_dpp v12, v12, v12 row_ror:4 row_mask:0xf bank_mask:0xf bound_ctrl:1
	v_add_f32_dpp v62, v62, v65 quad_perm:[1,0,3,2] row_mask:0xf bank_mask:0xf bound_ctrl:1
	v_cvt_pk_bf16_f32 v62, v62, v62
	v_add_f32_dpp v12, v12, v12 row_ror:8 row_mask:0xf bank_mask:0xf bound_ctrl:1
	v_pk_fma_f32 v[6:7], v[92:93], v[12:13], v[48:49] op_sel_hi:[1,0,1] neg_lo:[1,0,0] neg_hi:[1,0,0]
	v_pk_fma_f32 v[8:9], v[94:95], v[12:13], v[50:51] op_sel_hi:[1,0,1] neg_lo:[1,0,0] neg_hi:[1,0,0]
	ds_read_b128 v[20:23], v10 offset:49408
	ds_read_b128 v[28:31], v10 offset:49920
	ds_read_b128 v[24:27], v10 offset:49664
	s_waitcnt lgkmcnt(4)
	s_nop 0
	v_fma_mix_f32 v12, v6, v110, v180 op_sel_hi:[0,1,0]
	v_fma_mix_f32 v12, v7, v110, v12 op_sel:[0,1,0] op_sel_hi:[0,1,0]
	v_fma_mix_f32 v12, v8, v111, v12 op_sel_hi:[0,1,0]
	v_fma_mix_f32 v12, v9, v111, v12 op_sel:[0,1,0] op_sel_hi:[0,1,0]
	v_fma_mix_f32 v105, v6, v90, v180 op_sel_hi:[0,1,0]
	v_fma_mix_f32 v105, v7, v90, v105 op_sel:[0,1,0] op_sel_hi:[0,1,0]
	v_add_f32_dpp v12, v12, v12 row_ror:1 row_mask:0xf bank_mask:0xf bound_ctrl:1
	v_fma_mix_f32 v105, v8, v91, v105 op_sel_hi:[0,1,0]
	v_fma_mix_f32 v105, v9, v91, v105 op_sel:[0,1,0] op_sel_hi:[0,1,0]
	v_add_f32_dpp v12, v12, v12 row_ror:2 row_mask:0xf bank_mask:0xf bound_ctrl:1
	v_pk_fma_f32 v[48:49], v[118:119], v[72:73], v[6:7] op_sel:[0,1,0]
	v_pk_fma_f32 v[50:51], v[120:121], v[72:73], v[8:9] op_sel:[0,1,0]
	v_add_f32_dpp v12, v12, v12 row_ror:4 row_mask:0xf bank_mask:0xf bound_ctrl:1
	global_store_short v[2:3], v62, off
	v_lshl_add_u64 v[2:3], v[2:3], 0, s[84:85]
	v_add_f32_dpp v12, v12, v12 row_ror:8 row_mask:0xf bank_mask:0xf bound_ctrl:1
	v_pk_fma_f32 v[6:7], v[114:115], v[12:13], v[48:49] op_sel_hi:[1,0,1] neg_lo:[1,0,0] neg_hi:[1,0,0]
	v_pk_fma_f32 v[8:9], v[116:117], v[12:13], v[50:51] op_sel_hi:[1,0,1] neg_lo:[1,0,0] neg_hi:[1,0,0]
	v_pk_mul_f32 v[6:7], v[6:7], v[106:107]
	v_pk_mul_f32 v[8:9], v[8:9], v[108:109]
	ds_read_b128 v[36:39], v10 offset:50432
	ds_read_b128 v[44:47], v10 offset:50944
	ds_read_b128 v[40:43], v10 offset:50688
	s_waitcnt lgkmcnt(3)
	s_nop 0
	v_fma_mix_f32 v12, v6, v20, v180 op_sel_hi:[0,1,0]
	v_fma_mix_f32 v12, v7, v20, v12 op_sel:[0,1,0] op_sel_hi:[0,1,0]
	v_fma_mix_f32 v12, v8, v21, v12 op_sel_hi:[0,1,0]
	v_fma_mix_f32 v12, v9, v21, v12 op_sel:[0,1,0] op_sel_hi:[0,1,0]
	v_fma_mix_f32 v61, v6, v112, v180 op_sel_hi:[0,1,0]
	v_fma_mix_f32 v61, v7, v112, v61 op_sel:[0,1,0] op_sel_hi:[0,1,0]
	v_add_f32_dpp v12, v12, v12 row_ror:1 row_mask:0xf bank_mask:0xf bound_ctrl:1
	v_fma_mix_f32 v61, v8, v113, v61 op_sel_hi:[0,1,0]
	v_fma_mix_f32 v61, v9, v113, v61 op_sel:[0,1,0] op_sel_hi:[0,1,0]
	v_add_f32_dpp v12, v12, v12 row_ror:2 row_mask:0xf bank_mask:0xf bound_ctrl:1
	v_pk_fma_f32 v[48:49], v[28:29], v[66:67], v[6:7] op_sel_hi:[1,0,1]
	v_pk_fma_f32 v[50:51], v[30:31], v[66:67], v[8:9] op_sel_hi:[1,0,1]
	v_add_f32_dpp v12, v12, v12 row_ror:4 row_mask:0xf bank_mask:0xf bound_ctrl:1
	s_nop 1
	s_nop 0
	v_add_f32_dpp v12, v12, v12 row_ror:8 row_mask:0xf bank_mask:0xf bound_ctrl:1
	v_pk_fma_f32 v[6:7], v[24:25], v[12:13], v[48:49] op_sel_hi:[1,0,1] neg_lo:[1,0,0] neg_hi:[1,0,0]
	v_pk_fma_f32 v[8:9], v[26:27], v[12:13], v[50:51] op_sel_hi:[1,0,1] neg_lo:[1,0,0] neg_hi:[1,0,0]
	ds_read_b128 v[88:91], v10 offset:51456
	ds_read_b128 v[96:99], v10 offset:51968
	ds_read_b128 v[92:95], v10 offset:51712
	s_waitcnt lgkmcnt(3)
	s_nop 0
	v_fma_mix_f32 v12, v6, v36, v180 op_sel_hi:[0,1,0]
	v_fma_mix_f32 v12, v7, v36, v12 op_sel:[0,1,0] op_sel_hi:[0,1,0]
	v_fma_mix_f32 v12, v8, v37, v12 op_sel_hi:[0,1,0]
	v_fma_mix_f32 v12, v9, v37, v12 op_sel:[0,1,0] op_sel_hi:[0,1,0]
	v_fma_mix_f32 v122, v6, v22, v180 op_sel_hi:[0,1,0]
	v_fma_mix_f32 v122, v7, v22, v122 op_sel:[0,1,0] op_sel_hi:[0,1,0]
	v_add_f32_dpp v12, v12, v12 row_ror:1 row_mask:0xf bank_mask:0xf bound_ctrl:1
	v_fma_mix_f32 v122, v8, v23, v122 op_sel_hi:[0,1,0]
	v_fma_mix_f32 v122, v9, v23, v122 op_sel:[0,1,0] op_sel_hi:[0,1,0]
	v_add_f32_dpp v12, v12, v12 row_ror:2 row_mask:0xf bank_mask:0xf bound_ctrl:1
	v_pk_fma_f32 v[48:49], v[44:45], v[66:67], v[6:7] op_sel:[0,1,0]
	v_pk_fma_f32 v[50:51], v[46:47], v[66:67], v[8:9] op_sel:[0,1,0]
	v_add_f32_dpp v12, v12, v12 row_ror:4 row_mask:0xf bank_mask:0xf bound_ctrl:1
	v_add_f32_dpp v83, v83, v83 row_ror:8 row_mask:0xf bank_mask:0xc
	v_add_f32_dpp v83, v52, v52 row_ror:8 row_mask:0xf bank_mask:0x3
	v_add_f32_dpp v100, v100, v100 row_ror:8 row_mask:0xf bank_mask:0xc
	v_add_f32_dpp v12, v12, v12 row_ror:8 row_mask:0xf bank_mask:0xf bound_ctrl:1
	v_pk_fma_f32 v[6:7], v[40:41], v[12:13], v[48:49] op_sel_hi:[1,0,1] neg_lo:[1,0,0] neg_hi:[1,0,0]
	v_pk_fma_f32 v[8:9], v[42:43], v[12:13], v[50:51] op_sel_hi:[1,0,1] neg_lo:[1,0,0] neg_hi:[1,0,0]
	ds_read_b128 v[110:113], v10 offset:52480
	ds_read_b128 v[106:109], v10 offset:52224
	ds_read_b128 v[118:121], v10 offset:52992
	ds_read_b128 v[114:117], v10 offset:52736
	ds_read_b128 v[70:73], v11 offset:3328
	s_waitcnt lgkmcnt(5)
	s_nop 0
	v_fma_mix_f32 v12, v6, v88, v180 op_sel_hi:[0,1,0]
	v_fma_mix_f32 v12, v7, v88, v12 op_sel:[0,1,0] op_sel_hi:[0,1,0]
	v_fma_mix_f32 v12, v8, v89, v12 op_sel_hi:[0,1,0]
	v_fma_mix_f32 v12, v9, v89, v12 op_sel:[0,1,0] op_sel_hi:[0,1,0]
	v_fma_mix_f32 v123, v6, v38, v180 op_sel_hi:[0,1,0]
	v_fma_mix_f32 v123, v7, v38, v123 op_sel:[0,1,0] op_sel_hi:[0,1,0]
	v_add_f32_dpp v12, v12, v12 row_ror:1 row_mask:0xf bank_mask:0xf bound_ctrl:1
	v_fma_mix_f32 v123, v8, v39, v123 op_sel_hi:[0,1,0]
	v_fma_mix_f32 v123, v9, v39, v123 op_sel:[0,1,0] op_sel_hi:[0,1,0]
	v_add_f32_dpp v12, v12, v12 row_ror:2 row_mask:0xf bank_mask:0xf bound_ctrl:1
	v_pk_fma_f32 v[48:49], v[96:97], v[68:69], v[6:7] op_sel_hi:[1,0,1]
	v_pk_fma_f32 v[50:51], v[98:99], v[68:69], v[8:9] op_sel_hi:[1,0,1]
	v_add_f32_dpp v12, v12, v12 row_ror:4 row_mask:0xf bank_mask:0xf bound_ctrl:1
	v_add_f32_dpp v100, v53, v53 row_ror:8 row_mask:0xf bank_mask:0x3
	v_add_f32_dpp v101, v101, v101 row_ror:8 row_mask:0xf bank_mask:0xc
	v_add_f32_dpp v101, v54, v54 row_ror:8 row_mask:0xf bank_mask:0x3
	v_add_f32_dpp v12, v12, v12 row_ror:8 row_mask:0xf bank_mask:0xf bound_ctrl:1
	v_pk_fma_f32 v[6:7], v[92:93], v[12:13], v[48:49] op_sel_hi:[1,0,1] neg_lo:[1,0,0] neg_hi:[1,0,0]
	v_pk_fma_f32 v[8:9], v[94:95], v[12:13], v[50:51] op_sel_hi:[1,0,1] neg_lo:[1,0,0] neg_hi:[1,0,0]
	ds_read_b128 v[20:23], v10 offset:53504
	ds_read_b128 v[28:31], v10 offset:54016
	ds_read_b128 v[24:27], v10 offset:53760
	s_waitcnt lgkmcnt(4)
	s_nop 0
	v_fma_mix_f32 v12, v6, v110, v180 op_sel_hi:[0,1,0]
	v_fma_mix_f32 v12, v7, v110, v12 op_sel:[0,1,0] op_sel_hi:[0,1,0]
	v_fma_mix_f32 v12, v8, v111, v12 op_sel_hi:[0,1,0]
	v_fma_mix_f32 v12, v9, v111, v12 op_sel:[0,1,0] op_sel_hi:[0,1,0]
	v_fma_mix_f32 v124, v6, v90, v180 op_sel_hi:[0,1,0]
	v_fma_mix_f32 v124, v7, v90, v124 op_sel:[0,1,0] op_sel_hi:[0,1,0]
	v_add_f32_dpp v12, v12, v12 row_ror:1 row_mask:0xf bank_mask:0xf bound_ctrl:1
	v_fma_mix_f32 v124, v8, v91, v124 op_sel_hi:[0,1,0]
	v_fma_mix_f32 v124, v9, v91, v124 op_sel:[0,1,0] op_sel_hi:[0,1,0]
	v_add_f32_dpp v12, v12, v12 row_ror:2 row_mask:0xf bank_mask:0xf bound_ctrl:1
	v_pk_fma_f32 v[48:49], v[118:119], v[68:69], v[6:7] op_sel:[0,1,0]
	v_pk_fma_f32 v[50:51], v[120:121], v[68:69], v[8:9] op_sel:[0,1,0]
	v_add_f32_dpp v12, v12, v12 row_ror:4 row_mask:0xf bank_mask:0xf bound_ctrl:1
	v_add_f32_dpp v102, v102, v102 row_ror:8 row_mask:0xf bank_mask:0xc
	v_add_f32_dpp v102, v55, v55 row_ror:8 row_mask:0xf bank_mask:0x3
	v_add_f32_dpp v103, v103, v103 row_ror:8 row_mask:0xf bank_mask:0xc
	v_add_f32_dpp v12, v12, v12 row_ror:8 row_mask:0xf bank_mask:0xf bound_ctrl:1
	v_pk_fma_f32 v[6:7], v[114:115], v[12:13], v[48:49] op_sel_hi:[1,0,1] neg_lo:[1,0,0] neg_hi:[1,0,0]
	v_pk_fma_f32 v[8:9], v[116:117], v[12:13], v[50:51] op_sel_hi:[1,0,1] neg_lo:[1,0,0] neg_hi:[1,0,0]
	v_pk_mul_f32 v[6:7], v[6:7], v[106:107]
	v_pk_mul_f32 v[8:9], v[8:9], v[108:109]
	ds_read_b128 v[36:39], v10 offset:54528
	ds_read_b128 v[44:47], v10 offset:55040
	ds_read_b128 v[40:43], v10 offset:54784
	s_waitcnt lgkmcnt(3)
	s_nop 0
	v_fma_mix_f32 v12, v6, v20, v180 op_sel_hi:[0,1,0]
	v_fma_mix_f32 v12, v7, v20, v12 op_sel:[0,1,0] op_sel_hi:[0,1,0]
	v_fma_mix_f32 v12, v8, v21, v12 op_sel_hi:[0,1,0]
	v_fma_mix_f32 v12, v9, v21, v12 op_sel:[0,1,0] op_sel_hi:[0,1,0]
	v_fma_mix_f32 v125, v6, v112, v180 op_sel_hi:[0,1,0]
	v_fma_mix_f32 v125, v7, v112, v125 op_sel:[0,1,0] op_sel_hi:[0,1,0]
	v_add_f32_dpp v12, v12, v12 row_ror:1 row_mask:0xf bank_mask:0xf bound_ctrl:1
	v_fma_mix_f32 v125, v8, v113, v125 op_sel_hi:[0,1,0]
	v_fma_mix_f32 v125, v9, v113, v125 op_sel:[0,1,0] op_sel_hi:[0,1,0]
	v_add_f32_dpp v12, v12, v12 row_ror:2 row_mask:0xf bank_mask:0xf bound_ctrl:1
	v_pk_fma_f32 v[48:49], v[28:29], v[70:71], v[6:7] op_sel_hi:[1,0,1]
	v_pk_fma_f32 v[50:51], v[30:31], v[70:71], v[8:9] op_sel_hi:[1,0,1]
	v_add_f32_dpp v12, v12, v12 row_ror:4 row_mask:0xf bank_mask:0xf bound_ctrl:1
	v_add_f32_dpp v103, v56, v56 row_ror:8 row_mask:0xf bank_mask:0x3
	v_add_f32_dpp v104, v104, v104 row_ror:8 row_mask:0xf bank_mask:0xc
	v_add_f32_dpp v104, v57, v57 row_ror:8 row_mask:0xf bank_mask:0x3
	v_add_f32_dpp v12, v12, v12 row_ror:8 row_mask:0xf bank_mask:0xf bound_ctrl:1
	v_pk_fma_f32 v[6:7], v[24:25], v[12:13], v[48:49] op_sel_hi:[1,0,1] neg_lo:[1,0,0] neg_hi:[1,0,0]
	v_pk_fma_f32 v[8:9], v[26:27], v[12:13], v[50:51] op_sel_hi:[1,0,1] neg_lo:[1,0,0] neg_hi:[1,0,0]
	ds_read_b128 v[88:91], v10 offset:55552
	ds_read_b128 v[96:99], v10 offset:56064
	ds_read_b128 v[92:95], v10 offset:55808
	s_waitcnt lgkmcnt(3)
	s_nop 0
	v_fma_mix_f32 v12, v6, v36, v180 op_sel_hi:[0,1,0]
	v_fma_mix_f32 v12, v7, v36, v12 op_sel:[0,1,0] op_sel_hi:[0,1,0]
	v_fma_mix_f32 v12, v8, v37, v12 op_sel_hi:[0,1,0]
	v_fma_mix_f32 v12, v9, v37, v12 op_sel:[0,1,0] op_sel_hi:[0,1,0]
	v_fma_mix_f32 v126, v6, v22, v180 op_sel_hi:[0,1,0]
	v_fma_mix_f32 v126, v7, v22, v126 op_sel:[0,1,0] op_sel_hi:[0,1,0]
	v_add_f32_dpp v12, v12, v12 row_ror:1 row_mask:0xf bank_mask:0xf bound_ctrl:1
	v_fma_mix_f32 v126, v8, v23, v126 op_sel_hi:[0,1,0]
	v_fma_mix_f32 v126, v9, v23, v126 op_sel:[0,1,0] op_sel_hi:[0,1,0]
	v_add_f32_dpp v12, v12, v12 row_ror:2 row_mask:0xf bank_mask:0xf bound_ctrl:1
	v_pk_fma_f32 v[48:49], v[44:45], v[70:71], v[6:7] op_sel:[0,1,0]
	v_pk_fma_f32 v[50:51], v[46:47], v[70:71], v[8:9] op_sel:[0,1,0]
	v_add_f32_dpp v12, v12, v12 row_ror:4 row_mask:0xf bank_mask:0xf bound_ctrl:1
	v_add_f32_dpp v105, v105, v105 row_ror:8 row_mask:0xf bank_mask:0xc
	v_add_f32_dpp v105, v81, v81 row_ror:8 row_mask:0xf bank_mask:0x3
	v_add_f32_dpp v12, v12, v12 row_ror:8 row_mask:0xf bank_mask:0xf bound_ctrl:1
	v_pk_fma_f32 v[6:7], v[40:41], v[12:13], v[48:49] op_sel_hi:[1,0,1] neg_lo:[1,0,0] neg_hi:[1,0,0]
	v_pk_fma_f32 v[8:9], v[42:43], v[12:13], v[50:51] op_sel_hi:[1,0,1] neg_lo:[1,0,0] neg_hi:[1,0,0]
	ds_read_b128 v[110:113], v10 offset:56576
	ds_read_b128 v[106:109], v10 offset:56320
	ds_read_b128 v[118:121], v10 offset:57088
	ds_read_b128 v[114:117], v10 offset:56832
	ds_read_b128 v[66:69], v11 offset:3584
	s_waitcnt lgkmcnt(5)
	s_nop 0
	v_fma_mix_f32 v12, v6, v88, v180 op_sel_hi:[0,1,0]
	v_fma_mix_f32 v12, v7, v88, v12 op_sel:[0,1,0] op_sel_hi:[0,1,0]
	v_fma_mix_f32 v12, v8, v89, v12 op_sel_hi:[0,1,0]
	v_fma_mix_f32 v12, v9, v89, v12 op_sel:[0,1,0] op_sel_hi:[0,1,0]
	v_fma_mix_f32 v127, v6, v38, v180 op_sel_hi:[0,1,0]
	v_fma_mix_f32 v127, v7, v38, v127 op_sel:[0,1,0] op_sel_hi:[0,1,0]
	v_add_f32_dpp v12, v12, v12 row_ror:1 row_mask:0xf bank_mask:0xf bound_ctrl:1
	v_fma_mix_f32 v127, v8, v39, v127 op_sel_hi:[0,1,0]
	v_fma_mix_f32 v127, v9, v39, v127 op_sel:[0,1,0] op_sel_hi:[0,1,0]
	v_add_f32_dpp v12, v12, v12 row_ror:2 row_mask:0xf bank_mask:0xf bound_ctrl:1
	v_pk_fma_f32 v[48:49], v[96:97], v[72:73], v[6:7] op_sel_hi:[1,0,1]
	v_pk_fma_f32 v[50:51], v[98:99], v[72:73], v[8:9] op_sel_hi:[1,0,1]
	v_add_f32_dpp v12, v12, v12 row_ror:4 row_mask:0xf bank_mask:0xf bound_ctrl:1
	v_add_f32_dpp v61, v61, v61 row_ror:8 row_mask:0xf bank_mask:0xc
	v_add_f32_dpp v61, v82, v82 row_ror:8 row_mask:0xf bank_mask:0x3
	v_add_f32_dpp v12, v12, v12 row_ror:8 row_mask:0xf bank_mask:0xf bound_ctrl:1
	v_pk_fma_f32 v[6:7], v[92:93], v[12:13], v[48:49] op_sel_hi:[1,0,1] neg_lo:[1,0,0] neg_hi:[1,0,0]
	v_pk_fma_f32 v[8:9], v[94:95], v[12:13], v[50:51] op_sel_hi:[1,0,1] neg_lo:[1,0,0] neg_hi:[1,0,0]
	ds_read_b128 v[20:23], v10 offset:57600
	ds_read_b128 v[28:31], v10 offset:58112
	ds_read_b128 v[24:27], v10 offset:57856
	s_waitcnt lgkmcnt(4)
	s_nop 0
	v_fma_mix_f32 v12, v6, v110, v180 op_sel_hi:[0,1,0]
	v_fma_mix_f32 v12, v7, v110, v12 op_sel:[0,1,0] op_sel_hi:[0,1,0]
	v_fma_mix_f32 v12, v8, v111, v12 op_sel_hi:[0,1,0]
	v_fma_mix_f32 v12, v9, v111, v12 op_sel:[0,1,0] op_sel_hi:[0,1,0]
	v_fma_mix_f32 v128, v6, v90, v180 op_sel_hi:[0,1,0]
	v_fma_mix_f32 v128, v7, v90, v128 op_sel:[0,1,0] op_sel_hi:[0,1,0]
	v_add_f32_dpp v12, v12, v12 row_ror:1 row_mask:0xf bank_mask:0xf bound_ctrl:1
	v_fma_mix_f32 v128, v8, v91, v128 op_sel_hi:[0,1,0]
	v_fma_mix_f32 v128, v9, v91, v128 op_sel:[0,1,0] op_sel_hi:[0,1,0]
	v_add_f32_dpp v12, v12, v12 row_ror:2 row_mask:0xf bank_mask:0xf bound_ctrl:1
	v_pk_fma_f32 v[48:49], v[118:119], v[72:73], v[6:7] op_sel:[0,1,0]
	v_pk_fma_f32 v[50:51], v[120:121], v[72:73], v[8:9] op_sel:[0,1,0]
	v_add_f32_dpp v12, v12, v12 row_ror:4 row_mask:0xf bank_mask:0xf bound_ctrl:1
	v_add_f32_dpp v103, v103, v103 row_ror:4 row_mask:0xf bank_mask:0xa
	v_add_f32_dpp v103, v83, v83 row_ror:12 row_mask:0xf bank_mask:0x5
	v_add_f32_dpp v104, v104, v104 row_ror:4 row_mask:0xf bank_mask:0xa
	v_add_f32_dpp v12, v12, v12 row_ror:8 row_mask:0xf bank_mask:0xf bound_ctrl:1
	v_pk_fma_f32 v[6:7], v[114:115], v[12:13], v[48:49] op_sel_hi:[1,0,1] neg_lo:[1,0,0] neg_hi:[1,0,0]
	v_pk_fma_f32 v[8:9], v[116:117], v[12:13], v[50:51] op_sel_hi:[1,0,1] neg_lo:[1,0,0] neg_hi:[1,0,0]
	v_pk_mul_f32 v[6:7], v[6:7], v[106:107]
	v_pk_mul_f32 v[8:9], v[8:9], v[108:109]
	ds_read_b128 v[36:39], v10 offset:58624
	ds_read_b128 v[44:47], v10 offset:59136
	ds_read_b128 v[40:43], v10 offset:58880
	s_waitcnt lgkmcnt(3)
	s_nop 0
	v_fma_mix_f32 v12, v6, v20, v180 op_sel_hi:[0,1,0]
	v_fma_mix_f32 v12, v7, v20, v12 op_sel:[0,1,0] op_sel_hi:[0,1,0]
	v_fma_mix_f32 v12, v8, v21, v12 op_sel_hi:[0,1,0]
	v_fma_mix_f32 v12, v9, v21, v12 op_sel:[0,1,0] op_sel_hi:[0,1,0]
	v_fma_mix_f32 v129, v6, v112, v180 op_sel_hi:[0,1,0]
	v_fma_mix_f32 v129, v7, v112, v129 op_sel:[0,1,0] op_sel_hi:[0,1,0]
	v_add_f32_dpp v12, v12, v12 row_ror:1 row_mask:0xf bank_mask:0xf bound_ctrl:1
	v_fma_mix_f32 v129, v8, v113, v129 op_sel_hi:[0,1,0]
	v_fma_mix_f32 v129, v9, v113, v129 op_sel:[0,1,0] op_sel_hi:[0,1,0]
	v_add_f32_dpp v12, v12, v12 row_ror:2 row_mask:0xf bank_mask:0xf bound_ctrl:1
	v_pk_fma_f32 v[48:49], v[28:29], v[66:67], v[6:7] op_sel_hi:[1,0,1]
	v_pk_fma_f32 v[50:51], v[30:31], v[66:67], v[8:9] op_sel_hi:[1,0,1]
	v_add_f32_dpp v12, v12, v12 row_ror:4 row_mask:0xf bank_mask:0xf bound_ctrl:1
	v_add_f32_dpp v104, v100, v100 row_ror:12 row_mask:0xf bank_mask:0x5
	v_add_f32_dpp v105, v105, v105 row_ror:4 row_mask:0xf bank_mask:0xa
	v_add_f32_dpp v105, v101, v101 row_ror:12 row_mask:0xf bank_mask:0x5
	v_add_f32_dpp v12, v12, v12 row_ror:8 row_mask:0xf bank_mask:0xf bound_ctrl:1
	v_pk_fma_f32 v[6:7], v[24:25], v[12:13], v[48:49] op_sel_hi:[1,0,1] neg_lo:[1,0,0] neg_hi:[1,0,0]
	v_pk_fma_f32 v[8:9], v[26:27], v[12:13], v[50:51] op_sel_hi:[1,0,1] neg_lo:[1,0,0] neg_hi:[1,0,0]
	ds_read_b128 v[88:91], v10 offset:59648
	ds_read_b128 v[96:99], v10 offset:60160
	ds_read_b128 v[92:95], v10 offset:59904
	s_waitcnt lgkmcnt(3)
	s_nop 0
	v_fma_mix_f32 v12, v6, v36, v180 op_sel_hi:[0,1,0]
	v_fma_mix_f32 v12, v7, v36, v12 op_sel:[0,1,0] op_sel_hi:[0,1,0]
	v_fma_mix_f32 v12, v8, v37, v12 op_sel_hi:[0,1,0]
	v_fma_mix_f32 v12, v9, v37, v12 op_sel:[0,1,0] op_sel_hi:[0,1,0]
	v_fma_mix_f32 v130, v6, v22, v180 op_sel_hi:[0,1,0]
	v_fma_mix_f32 v130, v7, v22, v130 op_sel:[0,1,0] op_sel_hi:[0,1,0]
	v_add_f32_dpp v12, v12, v12 row_ror:1 row_mask:0xf bank_mask:0xf bound_ctrl:1
	v_fma_mix_f32 v130, v8, v23, v130 op_sel_hi:[0,1,0]
	v_fma_mix_f32 v130, v9, v23, v130 op_sel:[0,1,0] op_sel_hi:[0,1,0]
	v_add_f32_dpp v12, v12, v12 row_ror:2 row_mask:0xf bank_mask:0xf bound_ctrl:1
	v_pk_fma_f32 v[48:49], v[44:45], v[66:67], v[6:7] op_sel:[0,1,0]
	v_pk_fma_f32 v[50:51], v[46:47], v[66:67], v[8:9] op_sel:[0,1,0]
	v_add_f32_dpp v12, v12, v12 row_ror:4 row_mask:0xf bank_mask:0xf bound_ctrl:1
	v_add_f32_dpp v61, v61, v61 row_ror:4 row_mask:0xf bank_mask:0xa
	v_add_f32_dpp v61, v102, v102 row_ror:12 row_mask:0xf bank_mask:0x5
	v_add_f32_dpp v12, v12, v12 row_ror:8 row_mask:0xf bank_mask:0xf bound_ctrl:1
	v_pk_fma_f32 v[6:7], v[40:41], v[12:13], v[48:49] op_sel_hi:[1,0,1] neg_lo:[1,0,0] neg_hi:[1,0,0]
	v_pk_fma_f32 v[8:9], v[42:43], v[12:13], v[50:51] op_sel_hi:[1,0,1] neg_lo:[1,0,0] neg_hi:[1,0,0]
	ds_read_b128 v[110:113], v10 offset:60672
	ds_read_b128 v[106:109], v10 offset:60416
	ds_read_b128 v[118:121], v10 offset:61184
	ds_read_b128 v[114:117], v10 offset:60928
	ds_read_b128 v[70:73], v11 offset:3840
	s_waitcnt lgkmcnt(5)
	s_nop 0
	v_fma_mix_f32 v12, v6, v88, v180 op_sel_hi:[0,1,0]
	v_fma_mix_f32 v12, v7, v88, v12 op_sel:[0,1,0] op_sel_hi:[0,1,0]
	v_fma_mix_f32 v12, v8, v89, v12 op_sel_hi:[0,1,0]
	v_fma_mix_f32 v12, v9, v89, v12 op_sel:[0,1,0] op_sel_hi:[0,1,0]
	v_fma_mix_f32 v131, v6, v38, v180 op_sel_hi:[0,1,0]
	v_fma_mix_f32 v131, v7, v38, v131 op_sel:[0,1,0] op_sel_hi:[0,1,0]
	v_add_f32_dpp v12, v12, v12 row_ror:1 row_mask:0xf bank_mask:0xf bound_ctrl:1
	v_fma_mix_f32 v131, v8, v39, v131 op_sel_hi:[0,1,0]
	v_fma_mix_f32 v131, v9, v39, v131 op_sel:[0,1,0] op_sel_hi:[0,1,0]
	v_add_f32_dpp v12, v12, v12 row_ror:2 row_mask:0xf bank_mask:0xf bound_ctrl:1
	v_pk_fma_f32 v[48:49], v[96:97], v[68:69], v[6:7] op_sel_hi:[1,0,1]
	v_pk_fma_f32 v[50:51], v[98:99], v[68:69], v[8:9] op_sel_hi:[1,0,1]
	v_add_f32_dpp v12, v12, v12 row_ror:4 row_mask:0xf bank_mask:0xf bound_ctrl:1
	v_cndmask_b32_e64 v62, v105, v103, s[38:39]
	v_cndmask_b32_e64 v63, v103, v105, s[38:39]
	v_add_f32_dpp v12, v12, v12 row_ror:8 row_mask:0xf bank_mask:0xf bound_ctrl:1
	v_pk_fma_f32 v[6:7], v[92:93], v[12:13], v[48:49] op_sel_hi:[1,0,1] neg_lo:[1,0,0] neg_hi:[1,0,0]
	v_pk_fma_f32 v[8:9], v[94:95], v[12:13], v[50:51] op_sel_hi:[1,0,1] neg_lo:[1,0,0] neg_hi:[1,0,0]
	ds_read_b128 v[20:23], v10 offset:61696
	ds_read_b128 v[28:31], v10 offset:62208
	ds_read_b128 v[24:27], v10 offset:61952
	s_waitcnt lgkmcnt(4)
	s_nop 0
	v_fma_mix_f32 v12, v6, v110, v180 op_sel_hi:[0,1,0]
	v_fma_mix_f32 v12, v7, v110, v12 op_sel:[0,1,0] op_sel_hi:[0,1,0]
	v_fma_mix_f32 v12, v8, v111, v12 op_sel_hi:[0,1,0]
	v_fma_mix_f32 v12, v9, v111, v12 op_sel:[0,1,0] op_sel_hi:[0,1,0]
	v_fma_mix_f32 v132, v6, v90, v180 op_sel_hi:[0,1,0]
	v_fma_mix_f32 v132, v7, v90, v132 op_sel:[0,1,0] op_sel_hi:[0,1,0]
	v_add_f32_dpp v12, v12, v12 row_ror:1 row_mask:0xf bank_mask:0xf bound_ctrl:1
	v_fma_mix_f32 v132, v8, v91, v132 op_sel_hi:[0,1,0]
	v_fma_mix_f32 v132, v9, v91, v132 op_sel:[0,1,0] op_sel_hi:[0,1,0]
	v_add_f32_dpp v12, v12, v12 row_ror:2 row_mask:0xf bank_mask:0xf bound_ctrl:1
	v_pk_fma_f32 v[48:49], v[118:119], v[68:69], v[6:7] op_sel:[0,1,0]
	v_pk_fma_f32 v[50:51], v[120:121], v[68:69], v[8:9] op_sel:[0,1,0]
	v_add_f32_dpp v12, v12, v12 row_ror:4 row_mask:0xf bank_mask:0xf bound_ctrl:1
	v_cndmask_b32_e64 v64, v61, v104, s[38:39]
	v_cndmask_b32_e64 v65, v104, v61, s[38:39]
	v_add_f32_dpp v12, v12, v12 row_ror:8 row_mask:0xf bank_mask:0xf bound_ctrl:1
	v_pk_fma_f32 v[6:7], v[114:115], v[12:13], v[48:49] op_sel_hi:[1,0,1] neg_lo:[1,0,0] neg_hi:[1,0,0]
	v_pk_fma_f32 v[8:9], v[116:117], v[12:13], v[50:51] op_sel_hi:[1,0,1] neg_lo:[1,0,0] neg_hi:[1,0,0]
	v_pk_mul_f32 v[6:7], v[6:7], v[106:107]
	v_pk_mul_f32 v[8:9], v[8:9], v[108:109]
	ds_read_b128 v[36:39], v10 offset:62720
	ds_read_b128 v[44:47], v10 offset:63232
	ds_read_b128 v[40:43], v10 offset:62976
	s_waitcnt lgkmcnt(3)
	s_nop 0
	v_fma_mix_f32 v12, v6, v20, v180 op_sel_hi:[0,1,0]
	v_fma_mix_f32 v12, v7, v20, v12 op_sel:[0,1,0] op_sel_hi:[0,1,0]
	v_fma_mix_f32 v12, v8, v21, v12 op_sel_hi:[0,1,0]
	v_fma_mix_f32 v12, v9, v21, v12 op_sel:[0,1,0] op_sel_hi:[0,1,0]
	v_fma_mix_f32 v133, v6, v112, v180 op_sel_hi:[0,1,0]
	v_fma_mix_f32 v133, v7, v112, v133 op_sel:[0,1,0] op_sel_hi:[0,1,0]
	v_add_f32_dpp v12, v12, v12 row_ror:1 row_mask:0xf bank_mask:0xf bound_ctrl:1
	v_fma_mix_f32 v133, v8, v113, v133 op_sel_hi:[0,1,0]
	v_fma_mix_f32 v133, v9, v113, v133 op_sel:[0,1,0] op_sel_hi:[0,1,0]
	v_add_f32_dpp v12, v12, v12 row_ror:2 row_mask:0xf bank_mask:0xf bound_ctrl:1
	v_pk_fma_f32 v[48:49], v[28:29], v[70:71], v[6:7] op_sel_hi:[1,0,1]
	v_pk_fma_f32 v[50:51], v[30:31], v[70:71], v[8:9] op_sel_hi:[1,0,1]
	v_add_f32_dpp v12, v12, v12 row_ror:4 row_mask:0xf bank_mask:0xf bound_ctrl:1
	v_add_f32_dpp v62, v63, v62 quad_perm:[2,3,0,1] row_mask:0xf bank_mask:0xf bound_ctrl:1
	v_add_f32_dpp v63, v65, v64 quad_perm:[2,3,0,1] row_mask:0xf bank_mask:0xf bound_ctrl:1
	v_add_f32_dpp v12, v12, v12 row_ror:8 row_mask:0xf bank_mask:0xf bound_ctrl:1
	v_pk_fma_f32 v[6:7], v[24:25], v[12:13], v[48:49] op_sel_hi:[1,0,1] neg_lo:[1,0,0] neg_hi:[1,0,0]
	v_pk_fma_f32 v[8:9], v[26:27], v[12:13], v[50:51] op_sel_hi:[1,0,1] neg_lo:[1,0,0] neg_hi:[1,0,0]
	ds_read_b128 v[88:91], v10 offset:63744
	ds_read_b128 v[96:99], v10 offset:64256
	ds_read_b128 v[92:95], v10 offset:64000
	s_waitcnt lgkmcnt(3)
	s_nop 0
	v_fma_mix_f32 v12, v6, v36, v180 op_sel_hi:[0,1,0]
	v_fma_mix_f32 v12, v7, v36, v12 op_sel:[0,1,0] op_sel_hi:[0,1,0]
	v_fma_mix_f32 v12, v8, v37, v12 op_sel_hi:[0,1,0]
	v_fma_mix_f32 v12, v9, v37, v12 op_sel:[0,1,0] op_sel_hi:[0,1,0]
	v_fma_mix_f32 v134, v6, v22, v180 op_sel_hi:[0,1,0]
	v_fma_mix_f32 v134, v7, v22, v134 op_sel:[0,1,0] op_sel_hi:[0,1,0]
	v_add_f32_dpp v12, v12, v12 row_ror:1 row_mask:0xf bank_mask:0xf bound_ctrl:1
	v_fma_mix_f32 v134, v8, v23, v134 op_sel_hi:[0,1,0]
	v_fma_mix_f32 v134, v9, v23, v134 op_sel:[0,1,0] op_sel_hi:[0,1,0]
	v_add_f32_dpp v12, v12, v12 row_ror:2 row_mask:0xf bank_mask:0xf bound_ctrl:1
	v_pk_fma_f32 v[48:49], v[44:45], v[70:71], v[6:7] op_sel:[0,1,0]
	v_pk_fma_f32 v[50:51], v[46:47], v[70:71], v[8:9] op_sel:[0,1,0]
	v_add_f32_dpp v12, v12, v12 row_ror:4 row_mask:0xf bank_mask:0xf bound_ctrl:1
	v_cndmask_b32_e64 v65, v63, v62, s[40:41]
	v_cndmask_b32_e64 v62, v62, v63, s[40:41]
	v_add_f32_dpp v12, v12, v12 row_ror:8 row_mask:0xf bank_mask:0xf bound_ctrl:1
	v_pk_fma_f32 v[6:7], v[40:41], v[12:13], v[48:49] op_sel_hi:[1,0,1] neg_lo:[1,0,0] neg_hi:[1,0,0]
	v_pk_fma_f32 v[8:9], v[42:43], v[12:13], v[50:51] op_sel_hi:[1,0,1] neg_lo:[1,0,0] neg_hi:[1,0,0]
	ds_read_b128 v[110:113], v10 offset:64768
	ds_read_b128 v[106:109], v10 offset:64512
	ds_read_b128 v[118:121], v10 offset:65280
	ds_read_b128 v[114:117], v10 offset:65024
	s_waitcnt lgkmcnt(4)
	s_nop 0
	v_fma_mix_f32 v12, v6, v88, v180 op_sel_hi:[0,1,0]
	v_fma_mix_f32 v12, v7, v88, v12 op_sel:[0,1,0] op_sel_hi:[0,1,0]
	v_fma_mix_f32 v12, v8, v89, v12 op_sel_hi:[0,1,0]
	v_fma_mix_f32 v12, v9, v89, v12 op_sel:[0,1,0] op_sel_hi:[0,1,0]
	v_fma_mix_f32 v135, v6, v38, v180 op_sel_hi:[0,1,0]
	v_fma_mix_f32 v135, v7, v38, v135 op_sel:[0,1,0] op_sel_hi:[0,1,0]
	v_add_f32_dpp v12, v12, v12 row_ror:1 row_mask:0xf bank_mask:0xf bound_ctrl:1
	v_fma_mix_f32 v135, v8, v39, v135 op_sel_hi:[0,1,0]
	v_fma_mix_f32 v135, v9, v39, v135 op_sel:[0,1,0] op_sel_hi:[0,1,0]
	v_add_f32_dpp v12, v12, v12 row_ror:2 row_mask:0xf bank_mask:0xf bound_ctrl:1
	v_pk_fma_f32 v[48:49], v[96:97], v[72:73], v[6:7] op_sel_hi:[1,0,1]
	v_pk_fma_f32 v[50:51], v[98:99], v[72:73], v[8:9] op_sel_hi:[1,0,1]
	v_add_f32_dpp v12, v12, v12 row_ror:4 row_mask:0xf bank_mask:0xf bound_ctrl:1
	v_add_f32_dpp v62, v62, v65 quad_perm:[1,0,3,2] row_mask:0xf bank_mask:0xf bound_ctrl:1
	v_cvt_pk_bf16_f32 v62, v62, v62
	v_add_f32_dpp v12, v12, v12 row_ror:8 row_mask:0xf bank_mask:0xf bound_ctrl:1
	v_pk_fma_f32 v[6:7], v[92:93], v[12:13], v[48:49] op_sel_hi:[1,0,1] neg_lo:[1,0,0] neg_hi:[1,0,0]
	v_pk_fma_f32 v[8:9], v[94:95], v[12:13], v[50:51] op_sel_hi:[1,0,1] neg_lo:[1,0,0] neg_hi:[1,0,0]
	s_waitcnt lgkmcnt(0)
	s_barrier
	v_xor_b32_e32 v10, 0x10000, v10
	v_xor_b32_e32 v11, 0x1000, v11
	ds_read_b128 v[66:69], v11 offset:0
	ds_read_b128 v[20:23], v10 offset:256
	ds_read_b128 v[28:31], v10 offset:768
	ds_read_b128 v[24:27], v10 offset:512
	ds_read_b128 v[36:39], v10 offset:1280
	ds_read_b128 v[44:47], v10 offset:1792
	ds_read_b128 v[40:43], v10 offset:1536
	v_fma_mix_f32 v12, v6, v110, v180 op_sel_hi:[0,1,0]
	v_fma_mix_f32 v12, v7, v110, v12 op_sel:[0,1,0] op_sel_hi:[0,1,0]
	v_fma_mix_f32 v12, v8, v111, v12 op_sel_hi:[0,1,0]
	v_fma_mix_f32 v12, v9, v111, v12 op_sel:[0,1,0] op_sel_hi:[0,1,0]
	v_fma_mix_f32 v136, v6, v90, v180 op_sel_hi:[0,1,0]
	v_fma_mix_f32 v136, v7, v90, v136 op_sel:[0,1,0] op_sel_hi:[0,1,0]
	v_add_f32_dpp v12, v12, v12 row_ror:1 row_mask:0xf bank_mask:0xf bound_ctrl:1
	v_fma_mix_f32 v136, v8, v91, v136 op_sel_hi:[0,1,0]
	v_fma_mix_f32 v136, v9, v91, v136 op_sel:[0,1,0] op_sel_hi:[0,1,0]
	v_add_f32_dpp v12, v12, v12 row_ror:2 row_mask:0xf bank_mask:0xf bound_ctrl:1
	v_pk_fma_f32 v[48:49], v[118:119], v[72:73], v[6:7] op_sel:[0,1,0]
	v_pk_fma_f32 v[50:51], v[120:121], v[72:73], v[8:9] op_sel:[0,1,0]
	v_add_f32_dpp v12, v12, v12 row_ror:4 row_mask:0xf bank_mask:0xf bound_ctrl:1
	global_store_short v[2:3], v62, off
	v_lshl_add_u64 v[2:3], v[2:3], 0, s[84:85]
	v_add_f32_dpp v12, v12, v12 row_ror:8 row_mask:0xf bank_mask:0xf bound_ctrl:1
	v_pk_fma_f32 v[6:7], v[114:115], v[12:13], v[48:49] op_sel_hi:[1,0,1] neg_lo:[1,0,0] neg_hi:[1,0,0]
	v_pk_fma_f32 v[8:9], v[116:117], v[12:13], v[50:51] op_sel_hi:[1,0,1] neg_lo:[1,0,0] neg_hi:[1,0,0]
	v_pk_mul_f32 v[6:7], v[6:7], v[106:107]
	v_pk_mul_f32 v[8:9], v[8:9], v[108:109]
	v_fma_mix_f32 v137, v6, v112, v180 op_sel_hi:[0,1,0]
	v_fma_mix_f32 v137, v7, v112, v137 op_sel:[0,1,0] op_sel_hi:[0,1,0]
	v_fma_mix_f32 v137, v8, v113, v137 op_sel_hi:[0,1,0]
	v_fma_mix_f32 v137, v9, v113, v137 op_sel:[0,1,0] op_sel_hi:[0,1,0]
	v_mov_b32_e32 v170, v2
	v_mov_b32_e32 v171, v3
	s_mov_b64 s[100:101], -1
	s_nop 0
	s_cmp_lg_u32 s28, 0x800000
	s_cbranch_scc1 .Lscan_cons_chunk
	v_add_f32_dpp v130, v130, v130 row_ror:8 row_mask:0xf bank_mask:0xc
	v_add_f32_dpp v130, v122, v122 row_ror:8 row_mask:0xf bank_mask:0x3
	v_add_f32_dpp v131, v131, v131 row_ror:8 row_mask:0xf bank_mask:0xc
	v_add_f32_dpp v131, v123, v123 row_ror:8 row_mask:0xf bank_mask:0x3
	v_add_f32_dpp v132, v132, v132 row_ror:8 row_mask:0xf bank_mask:0xc
	v_add_f32_dpp v132, v124, v124 row_ror:8 row_mask:0xf bank_mask:0x3
	v_add_f32_dpp v133, v133, v133 row_ror:8 row_mask:0xf bank_mask:0xc
	v_add_f32_dpp v133, v125, v125 row_ror:8 row_mask:0xf bank_mask:0x3
	v_add_f32_dpp v134, v134, v134 row_ror:8 row_mask:0xf bank_mask:0xc
	v_add_f32_dpp v134, v126, v126 row_ror:8 row_mask:0xf bank_mask:0x3
	v_add_f32_dpp v135, v135, v135 row_ror:8 row_mask:0xf bank_mask:0xc
	v_add_f32_dpp v135, v127, v127 row_ror:8 row_mask:0xf bank_mask:0x3
	v_add_f32_dpp v136, v136, v136 row_ror:8 row_mask:0xf bank_mask:0xc
	v_add_f32_dpp v136, v128, v128 row_ror:8 row_mask:0xf bank_mask:0x3
	v_add_f32_dpp v137, v137, v137 row_ror:8 row_mask:0xf bank_mask:0xc
	v_add_f32_dpp v137, v129, v129 row_ror:8 row_mask:0xf bank_mask:0x3
	v_add_f32_dpp v134, v134, v134 row_ror:4 row_mask:0xf bank_mask:0xa
	v_add_f32_dpp v134, v130, v130 row_ror:12 row_mask:0xf bank_mask:0x5
	v_add_f32_dpp v135, v135, v135 row_ror:4 row_mask:0xf bank_mask:0xa
	v_add_f32_dpp v135, v131, v131 row_ror:12 row_mask:0xf bank_mask:0x5
	v_add_f32_dpp v136, v136, v136 row_ror:4 row_mask:0xf bank_mask:0xa
	v_add_f32_dpp v136, v132, v132 row_ror:12 row_mask:0xf bank_mask:0x5
	v_add_f32_dpp v137, v137, v137 row_ror:4 row_mask:0xf bank_mask:0xa
	v_add_f32_dpp v137, v133, v133 row_ror:12 row_mask:0xf bank_mask:0x5
	v_cndmask_b32_e64 v62, v136, v134, s[38:39]
	v_cndmask_b32_e64 v63, v134, v136, s[38:39]
	v_cndmask_b32_e64 v64, v137, v135, s[38:39]
	v_cndmask_b32_e64 v65, v135, v137, s[38:39]
	v_add_f32_dpp v62, v63, v62 quad_perm:[2,3,0,1] row_mask:0xf bank_mask:0xf bound_ctrl:1
	s_nop 0
	v_add_f32_dpp v63, v65, v64 quad_perm:[2,3,0,1] row_mask:0xf bank_mask:0xf bound_ctrl:1
	v_cndmask_b32_e64 v65, v63, v62, s[40:41]
	v_cndmask_b32_e64 v62, v62, v63, s[40:41]
	s_nop 1
	v_add_f32_dpp v62, v62, v65 quad_perm:[1,0,3,2] row_mask:0xf bank_mask:0xf bound_ctrl:1
	v_cvt_pk_bf16_f32 v62, v62, v62
	global_store_short v[2:3], v62, off
	s_branch .LBB0_53
